# conv LayerNorm tail: packed f32 for gain/bias FMA and SiLU, one wait per cross-lane round
# baseline (speedup 1.0000x reference)
; #define LAS __attribute__((address_space(3)))
;     static __device__ __forceinline__ void run(float (&acc)[32], const float (&wv)[31], const LAS float* U, int rb, int cch) {
;         const float uv = U[ring94(ring94(rb + S)) * 256 + cch];
; #pragma unroll
;         for (int o = 0; o < 32; ++o) { constexpr int dummy = 0; const int kk = S - o + dummy; if (kk >= 0 && kk <= 30) acc[o] += wv[kk] * uv; }
; __device__ __forceinline__ void conv_loop(unsigned char* ws_, const float* const* in_, int l_, LAS unsigned char* lds, int tid, int bid, int G) {
;     ...
;             float acc[32];
; #pragma unroll
;             for (int o = 0; o < 32; ++o) acc[o] = bias;
;             const int rb = base + 32 * half;
;             ConvStep<0>::run(acc, wv, U, rb, cch);
.LBB0_302:
	v_lshl_add_u32 v231, v103, 10, v104
	v_lshl_add_u64 v[46:47], v[46:47], 0, s[0:1]
	v_lshl_add_u64 v[64:65], v[64:65], 0, s[0:1]
	v_lshl_add_u64 v[66:67], v[66:67], 0, s[0:1]
	v_lshl_add_u64 v[68:69], v[68:69], 0, s[0:1]
	s_mov_b32 s2, 0x1e500000
	v_mul_u32_u24_e32 v229, 0x1e0, v103
	v_add_u32_e32 v229, v229, v104
	v_add_u32_e32 v230, 0x10000, v229
	ds_read2st64_b32 v[232:233], v231 offset0:0 offset1:4
	ds_read2st64_b32 v[234:235], v231 offset0:8 offset1:12
	ds_read2st64_b32 v[236:237], v231 offset0:16 offset1:20
	ds_read2st64_b32 v[238:239], v231 offset0:24 offset1:28
	v_mov_b32_e32 v192, v73
	v_mov_b32_e32 v193, v74
	v_mov_b32_e32 v194, v75
	v_mov_b32_e32 v195, v76
	v_mov_b32_e32 v196, v77
	v_mov_b32_e32 v197, v78
	v_mov_b32_e32 v198, v79
	v_mov_b32_e32 v199, v80
	v_mov_b32_e32 v200, v81
	v_mov_b32_e32 v201, v82
	v_mov_b32_e32 v202, v83
	v_mov_b32_e32 v203, v84
	v_mov_b32_e32 v204, v85
	v_mov_b32_e32 v205, v86
	v_mov_b32_e32 v206, v87
	v_mov_b32_e32 v207, v88
	v_mov_b32_e32 v208, v89
	v_mov_b32_e32 v209, v90
	v_mov_b32_e32 v210, v91
	v_mov_b32_e32 v211, v92
	v_mov_b32_e32 v212, v93
	v_mov_b32_e32 v213, v94
	v_mov_b32_e32 v166, v95
	v_mov_b32_e32 v167, v96
	v_mov_b32_e32 v168, v97
	v_mov_b32_e32 v169, v98
	v_mov_b32_e32 v170, v99
	v_mov_b32_e32 v171, v100
	v_mov_b32_e32 v172, v101
	v_mov_b32_e32 v173, v1
	v_mov_b32_e32 v124, v51
	v_mov_b32_e32 v125, v51
	v_mov_b32_e32 v126, v51
	v_mov_b32_e32 v127, v51
	v_mov_b32_e32 v128, v51
	v_mov_b32_e32 v129, v51
	v_mov_b32_e32 v130, v51
	v_mov_b32_e32 v131, v51
	v_mov_b32_e32 v132, v51
	v_mov_b32_e32 v133, v51
	v_mov_b32_e32 v134, v51
	v_mov_b32_e32 v135, v51
	v_mov_b32_e32 v136, v51
	v_mov_b32_e32 v137, v51
	v_mov_b32_e32 v148, v51
	v_mov_b32_e32 v149, v51
	v_mov_b32_e32 v150, v51
	v_mov_b32_e32 v151, v51
	v_mov_b32_e32 v152, v51
	v_mov_b32_e32 v153, v51
	v_mov_b32_e32 v154, v51
	v_mov_b32_e32 v155, v51
	v_mov_b32_e32 v156, v51
	v_mov_b32_e32 v157, v51
	v_mov_b32_e32 v158, v51
	v_mov_b32_e32 v159, v51
	v_mov_b32_e32 v160, v51
	v_mov_b32_e32 v161, v51
	v_mov_b32_e32 v162, v51
	v_mov_b32_e32 v163, v51
	v_mov_b32_e32 v164, v51
	v_mov_b32_e32 v165, v51
	ds_read2st64_b32 v[240:241], v231 offset0:32 offset1:36
	s_waitcnt lgkmcnt(4)
	v_fmac_f32_e32 v124, v1, v232
	v_pk_fma_f32 v[124:125], v[172:173], v[232:233], v[124:125] op_sel:[0,1,0]
	ds_read2st64_b32 v[232:233], v231 offset0:40 offset1:44
	s_waitcnt lgkmcnt(4)
	v_pk_fma_f32 v[124:125], v[100:101], v[234:235], v[124:125] op_sel_hi:[1,0,1]
	v_fmac_f32_e32 v126, v1, v234
	v_pk_fma_f32 v[124:125], v[170:171], v[234:235], v[124:125] op_sel:[0,1,0]
	v_pk_fma_f32 v[126:127], v[172:173], v[234:235], v[126:127] op_sel:[0,1,0]
	ds_read2st64_b32 v[234:235], v231 offset0:48 offset1:52
	s_waitcnt lgkmcnt(4)
	v_pk_fma_f32 v[124:125], v[98:99], v[236:237], v[124:125] op_sel_hi:[1,0,1]
	v_pk_fma_f32 v[126:127], v[100:101], v[236:237], v[126:127] op_sel_hi:[1,0,1]
	v_fmac_f32_e32 v128, v1, v236
	v_pk_fma_f32 v[124:125], v[168:169], v[236:237], v[124:125] op_sel:[0,1,0]
	v_pk_fma_f32 v[126:127], v[170:171], v[236:237], v[126:127] op_sel:[0,1,0]
	v_pk_fma_f32 v[128:129], v[172:173], v[236:237], v[128:129] op_sel:[0,1,0]
	ds_read2st64_b32 v[236:237], v231 offset0:56 offset1:60
	s_waitcnt lgkmcnt(4)
	v_pk_fma_f32 v[124:125], v[96:97], v[238:239], v[124:125] op_sel_hi:[1,0,1]
	v_pk_fma_f32 v[126:127], v[98:99], v[238:239], v[126:127] op_sel_hi:[1,0,1]
	v_pk_fma_f32 v[128:129], v[100:101], v[238:239], v[128:129] op_sel_hi:[1,0,1]
	v_fmac_f32_e32 v130, v1, v238
	v_pk_fma_f32 v[124:125], v[166:167], v[238:239], v[124:125] op_sel:[0,1,0]
	v_pk_fma_f32 v[126:127], v[168:169], v[238:239], v[126:127] op_sel:[0,1,0]
	v_pk_fma_f32 v[128:129], v[170:171], v[238:239], v[128:129] op_sel:[0,1,0]
	v_pk_fma_f32 v[130:131], v[172:173], v[238:239], v[130:131] op_sel:[0,1,0]
	ds_read2st64_b32 v[238:239], v231 offset0:64 offset1:68
	s_waitcnt lgkmcnt(4)
	v_pk_fma_f32 v[124:125], v[94:95], v[240:241], v[124:125] op_sel_hi:[1,0,1]
	v_pk_fma_f32 v[126:127], v[96:97], v[240:241], v[126:127] op_sel_hi:[1,0,1]
	v_pk_fma_f32 v[128:129], v[98:99], v[240:241], v[128:129] op_sel_hi:[1,0,1]
	v_pk_fma_f32 v[130:131], v[100:101], v[240:241], v[130:131] op_sel_hi:[1,0,1]
	v_fmac_f32_e32 v132, v1, v240
	v_pk_fma_f32 v[124:125], v[212:213], v[240:241], v[124:125] op_sel:[0,1,0]
	v_pk_fma_f32 v[126:127], v[166:167], v[240:241], v[126:127] op_sel:[0,1,0]
	v_pk_fma_f32 v[128:129], v[168:169], v[240:241], v[128:129] op_sel:[0,1,0]
	v_pk_fma_f32 v[130:131], v[170:171], v[240:241], v[130:131] op_sel:[0,1,0]
	v_pk_fma_f32 v[132:133], v[172:173], v[240:241], v[132:133] op_sel:[0,1,0]
	ds_read2st64_b32 v[240:241], v231 offset0:72 offset1:76
	s_waitcnt lgkmcnt(4)
	v_pk_fma_f32 v[124:125], v[92:93], v[232:233], v[124:125] op_sel_hi:[1,0,1]
	v_pk_fma_f32 v[126:127], v[94:95], v[232:233], v[126:127] op_sel_hi:[1,0,1]
	v_pk_fma_f32 v[128:129], v[96:97], v[232:233], v[128:129] op_sel_hi:[1,0,1]
	v_pk_fma_f32 v[130:131], v[98:99], v[232:233], v[130:131] op_sel_hi:[1,0,1]
	v_pk_fma_f32 v[132:133], v[100:101], v[232:233], v[132:133] op_sel_hi:[1,0,1]
	v_fmac_f32_e32 v134, v1, v232
	v_pk_fma_f32 v[124:125], v[210:211], v[232:233], v[124:125] op_sel:[0,1,0]
	v_pk_fma_f32 v[126:127], v[212:213], v[232:233], v[126:127] op_sel:[0,1,0]
	v_pk_fma_f32 v[128:129], v[166:167], v[232:233], v[128:129] op_sel:[0,1,0]
	v_pk_fma_f32 v[130:131], v[168:169], v[232:233], v[130:131] op_sel:[0,1,0]
	v_pk_fma_f32 v[132:133], v[170:171], v[232:233], v[132:133] op_sel:[0,1,0]
	v_pk_fma_f32 v[134:135], v[172:173], v[232:233], v[134:135] op_sel:[0,1,0]
	ds_read2st64_b32 v[232:233], v231 offset0:80 offset1:84
	s_waitcnt lgkmcnt(4)
; #define LAS __attribute__((address_space(3)))
;     static __device__ __forceinline__ void run(float (&acc)[32], const float (&wv)[31], const LAS float* U, int rb, int cch) {
;         const float uv = U[ring94(ring94(rb + S)) * 256 + cch];
; #pragma unroll
;         for (int o = 0; o < 32; ++o) { constexpr int dummy = 0; const int kk = S - o + dummy; if (kk >= 0 && kk <= 30) acc[o] += wv[kk] * uv; }
	v_pk_fma_f32 v[124:125], v[90:91], v[234:235], v[124:125] op_sel_hi:[1,0,1]
	v_pk_fma_f32 v[126:127], v[92:93], v[234:235], v[126:127] op_sel_hi:[1,0,1]
	v_pk_fma_f32 v[128:129], v[94:95], v[234:235], v[128:129] op_sel_hi:[1,0,1]
	v_pk_fma_f32 v[130:131], v[96:97], v[234:235], v[130:131] op_sel_hi:[1,0,1]
	v_pk_fma_f32 v[132:133], v[98:99], v[234:235], v[132:133] op_sel_hi:[1,0,1]
	v_pk_fma_f32 v[134:135], v[100:101], v[234:235], v[134:135] op_sel_hi:[1,0,1]
	v_fmac_f32_e32 v136, v1, v234
	v_pk_fma_f32 v[124:125], v[208:209], v[234:235], v[124:125] op_sel:[0,1,0]
	v_pk_fma_f32 v[126:127], v[210:211], v[234:235], v[126:127] op_sel:[0,1,0]
	v_pk_fma_f32 v[128:129], v[212:213], v[234:235], v[128:129] op_sel:[0,1,0]
	v_pk_fma_f32 v[130:131], v[166:167], v[234:235], v[130:131] op_sel:[0,1,0]
	v_pk_fma_f32 v[132:133], v[168:169], v[234:235], v[132:133] op_sel:[0,1,0]
	v_pk_fma_f32 v[134:135], v[170:171], v[234:235], v[134:135] op_sel:[0,1,0]
	v_pk_fma_f32 v[136:137], v[172:173], v[234:235], v[136:137] op_sel:[0,1,0]
	ds_read2st64_b32 v[234:235], v231 offset0:88 offset1:92
	s_waitcnt lgkmcnt(4)
	v_pk_fma_f32 v[124:125], v[88:89], v[236:237], v[124:125] op_sel_hi:[1,0,1]
	v_pk_fma_f32 v[126:127], v[90:91], v[236:237], v[126:127] op_sel_hi:[1,0,1]
	v_pk_fma_f32 v[128:129], v[92:93], v[236:237], v[128:129] op_sel_hi:[1,0,1]
	v_pk_fma_f32 v[130:131], v[94:95], v[236:237], v[130:131] op_sel_hi:[1,0,1]
	v_pk_fma_f32 v[132:133], v[96:97], v[236:237], v[132:133] op_sel_hi:[1,0,1]
	v_pk_fma_f32 v[134:135], v[98:99], v[236:237], v[134:135] op_sel_hi:[1,0,1]
	v_pk_fma_f32 v[136:137], v[100:101], v[236:237], v[136:137] op_sel_hi:[1,0,1]
	v_fmac_f32_e32 v148, v1, v236
	v_pk_fma_f32 v[124:125], v[206:207], v[236:237], v[124:125] op_sel:[0,1,0]
	v_pk_fma_f32 v[126:127], v[208:209], v[236:237], v[126:127] op_sel:[0,1,0]
	v_pk_fma_f32 v[128:129], v[210:211], v[236:237], v[128:129] op_sel:[0,1,0]
	v_pk_fma_f32 v[130:131], v[212:213], v[236:237], v[130:131] op_sel:[0,1,0]
	v_pk_fma_f32 v[132:133], v[166:167], v[236:237], v[132:133] op_sel:[0,1,0]
	v_pk_fma_f32 v[134:135], v[168:169], v[236:237], v[134:135] op_sel:[0,1,0]
	v_pk_fma_f32 v[136:137], v[170:171], v[236:237], v[136:137] op_sel:[0,1,0]
	v_pk_fma_f32 v[148:149], v[172:173], v[236:237], v[148:149] op_sel:[0,1,0]
	ds_read2st64_b32 v[236:237], v231 offset0:96 offset1:100
	s_waitcnt lgkmcnt(4)
	v_pk_fma_f32 v[124:125], v[86:87], v[238:239], v[124:125] op_sel_hi:[1,0,1]
	v_pk_fma_f32 v[126:127], v[88:89], v[238:239], v[126:127] op_sel_hi:[1,0,1]
	v_pk_fma_f32 v[128:129], v[90:91], v[238:239], v[128:129] op_sel_hi:[1,0,1]
	v_pk_fma_f32 v[130:131], v[92:93], v[238:239], v[130:131] op_sel_hi:[1,0,1]
	v_pk_fma_f32 v[132:133], v[94:95], v[238:239], v[132:133] op_sel_hi:[1,0,1]
	v_pk_fma_f32 v[134:135], v[96:97], v[238:239], v[134:135] op_sel_hi:[1,0,1]
	v_pk_fma_f32 v[136:137], v[98:99], v[238:239], v[136:137] op_sel_hi:[1,0,1]
	v_pk_fma_f32 v[148:149], v[100:101], v[238:239], v[148:149] op_sel_hi:[1,0,1]
	v_fmac_f32_e32 v150, v1, v238
	v_pk_fma_f32 v[124:125], v[204:205], v[238:239], v[124:125] op_sel:[0,1,0]
	v_pk_fma_f32 v[126:127], v[206:207], v[238:239], v[126:127] op_sel:[0,1,0]
	v_pk_fma_f32 v[128:129], v[208:209], v[238:239], v[128:129] op_sel:[0,1,0]
	v_pk_fma_f32 v[130:131], v[210:211], v[238:239], v[130:131] op_sel:[0,1,0]
	v_pk_fma_f32 v[132:133], v[212:213], v[238:239], v[132:133] op_sel:[0,1,0]
	v_pk_fma_f32 v[134:135], v[166:167], v[238:239], v[134:135] op_sel:[0,1,0]
	v_pk_fma_f32 v[136:137], v[168:169], v[238:239], v[136:137] op_sel:[0,1,0]
	v_pk_fma_f32 v[148:149], v[170:171], v[238:239], v[148:149] op_sel:[0,1,0]
	v_pk_fma_f32 v[150:151], v[172:173], v[238:239], v[150:151] op_sel:[0,1,0]
	ds_read2st64_b32 v[238:239], v231 offset0:104 offset1:108
	s_waitcnt lgkmcnt(4)
	v_pk_fma_f32 v[124:125], v[84:85], v[240:241], v[124:125] op_sel_hi:[1,0,1]
	v_pk_fma_f32 v[126:127], v[86:87], v[240:241], v[126:127] op_sel_hi:[1,0,1]
	v_pk_fma_f32 v[128:129], v[88:89], v[240:241], v[128:129] op_sel_hi:[1,0,1]
	v_pk_fma_f32 v[130:131], v[90:91], v[240:241], v[130:131] op_sel_hi:[1,0,1]
	v_pk_fma_f32 v[132:133], v[92:93], v[240:241], v[132:133] op_sel_hi:[1,0,1]
	v_pk_fma_f32 v[134:135], v[94:95], v[240:241], v[134:135] op_sel_hi:[1,0,1]
	v_pk_fma_f32 v[136:137], v[96:97], v[240:241], v[136:137] op_sel_hi:[1,0,1]
	v_pk_fma_f32 v[148:149], v[98:99], v[240:241], v[148:149] op_sel_hi:[1,0,1]
	v_pk_fma_f32 v[150:151], v[100:101], v[240:241], v[150:151] op_sel_hi:[1,0,1]
	v_fmac_f32_e32 v152, v1, v240
	v_pk_fma_f32 v[124:125], v[202:203], v[240:241], v[124:125] op_sel:[0,1,0]
	v_pk_fma_f32 v[126:127], v[204:205], v[240:241], v[126:127] op_sel:[0,1,0]
	v_pk_fma_f32 v[128:129], v[206:207], v[240:241], v[128:129] op_sel:[0,1,0]
	v_pk_fma_f32 v[130:131], v[208:209], v[240:241], v[130:131] op_sel:[0,1,0]
	v_pk_fma_f32 v[132:133], v[210:211], v[240:241], v[132:133] op_sel:[0,1,0]
	v_pk_fma_f32 v[134:135], v[212:213], v[240:241], v[134:135] op_sel:[0,1,0]
	v_pk_fma_f32 v[136:137], v[166:167], v[240:241], v[136:137] op_sel:[0,1,0]
	v_pk_fma_f32 v[148:149], v[168:169], v[240:241], v[148:149] op_sel:[0,1,0]
	v_pk_fma_f32 v[150:151], v[170:171], v[240:241], v[150:151] op_sel:[0,1,0]
	v_pk_fma_f32 v[152:153], v[172:173], v[240:241], v[152:153] op_sel:[0,1,0]
	ds_read2st64_b32 v[240:241], v231 offset0:112 offset1:116
	s_waitcnt lgkmcnt(4)
; #define LAS __attribute__((address_space(3)))
;     static __device__ __forceinline__ void run(float (&acc)[32], const float (&wv)[31], const LAS float* U, int rb, int cch) {
;         const float uv = U[ring94(ring94(rb + S)) * 256 + cch];
; #pragma unroll
;         for (int o = 0; o < 32; ++o) { constexpr int dummy = 0; const int kk = S - o + dummy; if (kk >= 0 && kk <= 30) acc[o] += wv[kk] * uv; }
	v_pk_fma_f32 v[124:125], v[82:83], v[232:233], v[124:125] op_sel_hi:[1,0,1]
	v_pk_fma_f32 v[126:127], v[84:85], v[232:233], v[126:127] op_sel_hi:[1,0,1]
	v_pk_fma_f32 v[128:129], v[86:87], v[232:233], v[128:129] op_sel_hi:[1,0,1]
	v_pk_fma_f32 v[130:131], v[88:89], v[232:233], v[130:131] op_sel_hi:[1,0,1]
	v_pk_fma_f32 v[132:133], v[90:91], v[232:233], v[132:133] op_sel_hi:[1,0,1]
	v_pk_fma_f32 v[134:135], v[92:93], v[232:233], v[134:135] op_sel_hi:[1,0,1]
	v_pk_fma_f32 v[136:137], v[94:95], v[232:233], v[136:137] op_sel_hi:[1,0,1]
	v_pk_fma_f32 v[148:149], v[96:97], v[232:233], v[148:149] op_sel_hi:[1,0,1]
	v_pk_fma_f32 v[150:151], v[98:99], v[232:233], v[150:151] op_sel_hi:[1,0,1]
	v_pk_fma_f32 v[152:153], v[100:101], v[232:233], v[152:153] op_sel_hi:[1,0,1]
	v_fmac_f32_e32 v154, v1, v232
	v_pk_fma_f32 v[124:125], v[200:201], v[232:233], v[124:125] op_sel:[0,1,0]
	v_pk_fma_f32 v[126:127], v[202:203], v[232:233], v[126:127] op_sel:[0,1,0]
	v_pk_fma_f32 v[128:129], v[204:205], v[232:233], v[128:129] op_sel:[0,1,0]
	v_pk_fma_f32 v[130:131], v[206:207], v[232:233], v[130:131] op_sel:[0,1,0]
	v_pk_fma_f32 v[132:133], v[208:209], v[232:233], v[132:133] op_sel:[0,1,0]
	v_pk_fma_f32 v[134:135], v[210:211], v[232:233], v[134:135] op_sel:[0,1,0]
	v_pk_fma_f32 v[136:137], v[212:213], v[232:233], v[136:137] op_sel:[0,1,0]
	v_pk_fma_f32 v[148:149], v[166:167], v[232:233], v[148:149] op_sel:[0,1,0]
	v_pk_fma_f32 v[150:151], v[168:169], v[232:233], v[150:151] op_sel:[0,1,0]
	v_pk_fma_f32 v[152:153], v[170:171], v[232:233], v[152:153] op_sel:[0,1,0]
	v_pk_fma_f32 v[154:155], v[172:173], v[232:233], v[154:155] op_sel:[0,1,0]
	ds_read2st64_b32 v[232:233], v231 offset0:120 offset1:124
	s_waitcnt lgkmcnt(4)
	v_pk_fma_f32 v[124:125], v[80:81], v[234:235], v[124:125] op_sel_hi:[1,0,1]
	v_pk_fma_f32 v[126:127], v[82:83], v[234:235], v[126:127] op_sel_hi:[1,0,1]
	v_pk_fma_f32 v[128:129], v[84:85], v[234:235], v[128:129] op_sel_hi:[1,0,1]
	v_pk_fma_f32 v[130:131], v[86:87], v[234:235], v[130:131] op_sel_hi:[1,0,1]
	v_pk_fma_f32 v[132:133], v[88:89], v[234:235], v[132:133] op_sel_hi:[1,0,1]
	v_pk_fma_f32 v[134:135], v[90:91], v[234:235], v[134:135] op_sel_hi:[1,0,1]
	v_pk_fma_f32 v[136:137], v[92:93], v[234:235], v[136:137] op_sel_hi:[1,0,1]
	v_pk_fma_f32 v[148:149], v[94:95], v[234:235], v[148:149] op_sel_hi:[1,0,1]
	v_pk_fma_f32 v[150:151], v[96:97], v[234:235], v[150:151] op_sel_hi:[1,0,1]
	v_pk_fma_f32 v[152:153], v[98:99], v[234:235], v[152:153] op_sel_hi:[1,0,1]
	v_pk_fma_f32 v[154:155], v[100:101], v[234:235], v[154:155] op_sel_hi:[1,0,1]
	v_fmac_f32_e32 v156, v1, v234
	v_pk_fma_f32 v[124:125], v[198:199], v[234:235], v[124:125] op_sel:[0,1,0]
	v_pk_fma_f32 v[126:127], v[200:201], v[234:235], v[126:127] op_sel:[0,1,0]
	v_pk_fma_f32 v[128:129], v[202:203], v[234:235], v[128:129] op_sel:[0,1,0]
	v_pk_fma_f32 v[130:131], v[204:205], v[234:235], v[130:131] op_sel:[0,1,0]
	v_pk_fma_f32 v[132:133], v[206:207], v[234:235], v[132:133] op_sel:[0,1,0]
	v_pk_fma_f32 v[134:135], v[208:209], v[234:235], v[134:135] op_sel:[0,1,0]
	v_pk_fma_f32 v[136:137], v[210:211], v[234:235], v[136:137] op_sel:[0,1,0]
	v_pk_fma_f32 v[148:149], v[212:213], v[234:235], v[148:149] op_sel:[0,1,0]
	v_pk_fma_f32 v[150:151], v[166:167], v[234:235], v[150:151] op_sel:[0,1,0]
	v_pk_fma_f32 v[152:153], v[168:169], v[234:235], v[152:153] op_sel:[0,1,0]
	v_pk_fma_f32 v[154:155], v[170:171], v[234:235], v[154:155] op_sel:[0,1,0]
	v_pk_fma_f32 v[156:157], v[172:173], v[234:235], v[156:157] op_sel:[0,1,0]
	ds_read2st64_b32 v[234:235], v231 offset0:128 offset1:132
	s_waitcnt lgkmcnt(4)
	v_pk_fma_f32 v[124:125], v[78:79], v[236:237], v[124:125] op_sel_hi:[1,0,1]
	v_pk_fma_f32 v[126:127], v[80:81], v[236:237], v[126:127] op_sel_hi:[1,0,1]
	v_pk_fma_f32 v[128:129], v[82:83], v[236:237], v[128:129] op_sel_hi:[1,0,1]
	v_pk_fma_f32 v[130:131], v[84:85], v[236:237], v[130:131] op_sel_hi:[1,0,1]
	v_pk_fma_f32 v[132:133], v[86:87], v[236:237], v[132:133] op_sel_hi:[1,0,1]
	v_pk_fma_f32 v[134:135], v[88:89], v[236:237], v[134:135] op_sel_hi:[1,0,1]
	v_pk_fma_f32 v[136:137], v[90:91], v[236:237], v[136:137] op_sel_hi:[1,0,1]
	v_pk_fma_f32 v[148:149], v[92:93], v[236:237], v[148:149] op_sel_hi:[1,0,1]
	v_pk_fma_f32 v[150:151], v[94:95], v[236:237], v[150:151] op_sel_hi:[1,0,1]
	v_pk_fma_f32 v[152:153], v[96:97], v[236:237], v[152:153] op_sel_hi:[1,0,1]
	v_pk_fma_f32 v[154:155], v[98:99], v[236:237], v[154:155] op_sel_hi:[1,0,1]
	v_pk_fma_f32 v[156:157], v[100:101], v[236:237], v[156:157] op_sel_hi:[1,0,1]
	v_fmac_f32_e32 v158, v1, v236
	v_pk_fma_f32 v[124:125], v[196:197], v[236:237], v[124:125] op_sel:[0,1,0]
	v_pk_fma_f32 v[126:127], v[198:199], v[236:237], v[126:127] op_sel:[0,1,0]
	v_pk_fma_f32 v[128:129], v[200:201], v[236:237], v[128:129] op_sel:[0,1,0]
	v_pk_fma_f32 v[130:131], v[202:203], v[236:237], v[130:131] op_sel:[0,1,0]
	v_pk_fma_f32 v[132:133], v[204:205], v[236:237], v[132:133] op_sel:[0,1,0]
	v_pk_fma_f32 v[134:135], v[206:207], v[236:237], v[134:135] op_sel:[0,1,0]
	v_pk_fma_f32 v[136:137], v[208:209], v[236:237], v[136:137] op_sel:[0,1,0]
	v_pk_fma_f32 v[148:149], v[210:211], v[236:237], v[148:149] op_sel:[0,1,0]
	v_pk_fma_f32 v[150:151], v[212:213], v[236:237], v[150:151] op_sel:[0,1,0]
	v_pk_fma_f32 v[152:153], v[166:167], v[236:237], v[152:153] op_sel:[0,1,0]
	v_pk_fma_f32 v[154:155], v[168:169], v[236:237], v[154:155] op_sel:[0,1,0]
	v_pk_fma_f32 v[156:157], v[170:171], v[236:237], v[156:157] op_sel:[0,1,0]
	v_pk_fma_f32 v[158:159], v[172:173], v[236:237], v[158:159] op_sel:[0,1,0]
	ds_read2st64_b32 v[236:237], v231 offset0:136 offset1:140
	s_waitcnt lgkmcnt(4)
; #define LAS __attribute__((address_space(3)))
;     static __device__ __forceinline__ void run(float (&acc)[32], const float (&wv)[31], const LAS float* U, int rb, int cch) {
;         const float uv = U[ring94(ring94(rb + S)) * 256 + cch];
; #pragma unroll
;         for (int o = 0; o < 32; ++o) { constexpr int dummy = 0; const int kk = S - o + dummy; if (kk >= 0 && kk <= 30) acc[o] += wv[kk] * uv; }
	v_pk_fma_f32 v[124:125], v[76:77], v[238:239], v[124:125] op_sel_hi:[1,0,1]
	v_pk_fma_f32 v[126:127], v[78:79], v[238:239], v[126:127] op_sel_hi:[1,0,1]
	v_pk_fma_f32 v[128:129], v[80:81], v[238:239], v[128:129] op_sel_hi:[1,0,1]
	v_pk_fma_f32 v[130:131], v[82:83], v[238:239], v[130:131] op_sel_hi:[1,0,1]
	v_pk_fma_f32 v[132:133], v[84:85], v[238:239], v[132:133] op_sel_hi:[1,0,1]
	v_pk_fma_f32 v[134:135], v[86:87], v[238:239], v[134:135] op_sel_hi:[1,0,1]
	v_pk_fma_f32 v[136:137], v[88:89], v[238:239], v[136:137] op_sel_hi:[1,0,1]
	v_pk_fma_f32 v[148:149], v[90:91], v[238:239], v[148:149] op_sel_hi:[1,0,1]
	v_pk_fma_f32 v[150:151], v[92:93], v[238:239], v[150:151] op_sel_hi:[1,0,1]
	v_pk_fma_f32 v[152:153], v[94:95], v[238:239], v[152:153] op_sel_hi:[1,0,1]
	v_pk_fma_f32 v[154:155], v[96:97], v[238:239], v[154:155] op_sel_hi:[1,0,1]
	v_pk_fma_f32 v[156:157], v[98:99], v[238:239], v[156:157] op_sel_hi:[1,0,1]
	v_pk_fma_f32 v[158:159], v[100:101], v[238:239], v[158:159] op_sel_hi:[1,0,1]
	v_fmac_f32_e32 v160, v1, v238
	v_pk_fma_f32 v[124:125], v[194:195], v[238:239], v[124:125] op_sel:[0,1,0]
	v_pk_fma_f32 v[126:127], v[196:197], v[238:239], v[126:127] op_sel:[0,1,0]
	v_pk_fma_f32 v[128:129], v[198:199], v[238:239], v[128:129] op_sel:[0,1,0]
	v_pk_fma_f32 v[130:131], v[200:201], v[238:239], v[130:131] op_sel:[0,1,0]
	v_pk_fma_f32 v[132:133], v[202:203], v[238:239], v[132:133] op_sel:[0,1,0]
	v_pk_fma_f32 v[134:135], v[204:205], v[238:239], v[134:135] op_sel:[0,1,0]
	v_pk_fma_f32 v[136:137], v[206:207], v[238:239], v[136:137] op_sel:[0,1,0]
	v_pk_fma_f32 v[148:149], v[208:209], v[238:239], v[148:149] op_sel:[0,1,0]
	v_pk_fma_f32 v[150:151], v[210:211], v[238:239], v[150:151] op_sel:[0,1,0]
	v_pk_fma_f32 v[152:153], v[212:213], v[238:239], v[152:153] op_sel:[0,1,0]
	v_pk_fma_f32 v[154:155], v[166:167], v[238:239], v[154:155] op_sel:[0,1,0]
	v_pk_fma_f32 v[156:157], v[168:169], v[238:239], v[156:157] op_sel:[0,1,0]
	v_pk_fma_f32 v[158:159], v[170:171], v[238:239], v[158:159] op_sel:[0,1,0]
	v_pk_fma_f32 v[160:161], v[172:173], v[238:239], v[160:161] op_sel:[0,1,0]
	ds_read2st64_b32 v[238:239], v231 offset0:144 offset1:148
	s_waitcnt lgkmcnt(4)
	v_pk_fma_f32 v[124:125], v[74:75], v[240:241], v[124:125] op_sel_hi:[1,0,1]
	v_pk_fma_f32 v[126:127], v[76:77], v[240:241], v[126:127] op_sel_hi:[1,0,1]
	v_pk_fma_f32 v[128:129], v[78:79], v[240:241], v[128:129] op_sel_hi:[1,0,1]
	v_pk_fma_f32 v[130:131], v[80:81], v[240:241], v[130:131] op_sel_hi:[1,0,1]
	v_pk_fma_f32 v[132:133], v[82:83], v[240:241], v[132:133] op_sel_hi:[1,0,1]
	v_pk_fma_f32 v[134:135], v[84:85], v[240:241], v[134:135] op_sel_hi:[1,0,1]
	v_pk_fma_f32 v[136:137], v[86:87], v[240:241], v[136:137] op_sel_hi:[1,0,1]
	v_pk_fma_f32 v[148:149], v[88:89], v[240:241], v[148:149] op_sel_hi:[1,0,1]
	v_pk_fma_f32 v[150:151], v[90:91], v[240:241], v[150:151] op_sel_hi:[1,0,1]
	v_pk_fma_f32 v[152:153], v[92:93], v[240:241], v[152:153] op_sel_hi:[1,0,1]
	v_pk_fma_f32 v[154:155], v[94:95], v[240:241], v[154:155] op_sel_hi:[1,0,1]
	v_pk_fma_f32 v[156:157], v[96:97], v[240:241], v[156:157] op_sel_hi:[1,0,1]
	v_pk_fma_f32 v[158:159], v[98:99], v[240:241], v[158:159] op_sel_hi:[1,0,1]
	v_pk_fma_f32 v[160:161], v[100:101], v[240:241], v[160:161] op_sel_hi:[1,0,1]
	v_fmac_f32_e32 v162, v1, v240
	v_pk_fma_f32 v[124:125], v[192:193], v[240:241], v[124:125] op_sel:[0,1,0]
	v_pk_fma_f32 v[126:127], v[194:195], v[240:241], v[126:127] op_sel:[0,1,0]
	v_pk_fma_f32 v[128:129], v[196:197], v[240:241], v[128:129] op_sel:[0,1,0]
	v_pk_fma_f32 v[130:131], v[198:199], v[240:241], v[130:131] op_sel:[0,1,0]
	v_pk_fma_f32 v[132:133], v[200:201], v[240:241], v[132:133] op_sel:[0,1,0]
	v_pk_fma_f32 v[134:135], v[202:203], v[240:241], v[134:135] op_sel:[0,1,0]
	v_pk_fma_f32 v[136:137], v[204:205], v[240:241], v[136:137] op_sel:[0,1,0]
	v_pk_fma_f32 v[148:149], v[206:207], v[240:241], v[148:149] op_sel:[0,1,0]
	v_pk_fma_f32 v[150:151], v[208:209], v[240:241], v[150:151] op_sel:[0,1,0]
	v_pk_fma_f32 v[152:153], v[210:211], v[240:241], v[152:153] op_sel:[0,1,0]
	v_pk_fma_f32 v[154:155], v[212:213], v[240:241], v[154:155] op_sel:[0,1,0]
	v_pk_fma_f32 v[156:157], v[166:167], v[240:241], v[156:157] op_sel:[0,1,0]
	v_pk_fma_f32 v[158:159], v[168:169], v[240:241], v[158:159] op_sel:[0,1,0]
	v_pk_fma_f32 v[160:161], v[170:171], v[240:241], v[160:161] op_sel:[0,1,0]
	v_pk_fma_f32 v[162:163], v[172:173], v[240:241], v[162:163] op_sel:[0,1,0]
	ds_read2st64_b32 v[240:241], v231 offset0:152 offset1:156
	s_waitcnt lgkmcnt(4)
; #define LAS __attribute__((address_space(3)))
;     static __device__ __forceinline__ void run(float (&acc)[32], const float (&wv)[31], const LAS float* U, int rb, int cch) {
;         const float uv = U[ring94(ring94(rb + S)) * 256 + cch];
; #pragma unroll
;         for (int o = 0; o < 32; ++o) { constexpr int dummy = 0; const int kk = S - o + dummy; if (kk >= 0 && kk <= 30) acc[o] += wv[kk] * uv; }
	v_pk_fma_f32 v[124:125], v[72:73], v[232:233], v[124:125] op_sel_hi:[1,0,1]
	v_pk_fma_f32 v[126:127], v[74:75], v[232:233], v[126:127] op_sel_hi:[1,0,1]
	v_pk_fma_f32 v[128:129], v[76:77], v[232:233], v[128:129] op_sel_hi:[1,0,1]
	v_pk_fma_f32 v[130:131], v[78:79], v[232:233], v[130:131] op_sel_hi:[1,0,1]
	v_pk_fma_f32 v[132:133], v[80:81], v[232:233], v[132:133] op_sel_hi:[1,0,1]
	v_pk_fma_f32 v[134:135], v[82:83], v[232:233], v[134:135] op_sel_hi:[1,0,1]
	v_pk_fma_f32 v[136:137], v[84:85], v[232:233], v[136:137] op_sel_hi:[1,0,1]
	v_pk_fma_f32 v[148:149], v[86:87], v[232:233], v[148:149] op_sel_hi:[1,0,1]
	v_pk_fma_f32 v[150:151], v[88:89], v[232:233], v[150:151] op_sel_hi:[1,0,1]
	v_pk_fma_f32 v[152:153], v[90:91], v[232:233], v[152:153] op_sel_hi:[1,0,1]
	v_pk_fma_f32 v[154:155], v[92:93], v[232:233], v[154:155] op_sel_hi:[1,0,1]
	v_pk_fma_f32 v[156:157], v[94:95], v[232:233], v[156:157] op_sel_hi:[1,0,1]
	v_pk_fma_f32 v[158:159], v[96:97], v[232:233], v[158:159] op_sel_hi:[1,0,1]
	v_pk_fma_f32 v[160:161], v[98:99], v[232:233], v[160:161] op_sel_hi:[1,0,1]
	v_pk_fma_f32 v[162:163], v[100:101], v[232:233], v[162:163] op_sel_hi:[1,0,1]
	v_fmac_f32_e32 v164, v1, v232
	v_fmac_f32_e32 v125, v72, v233
	v_pk_fma_f32 v[126:127], v[192:193], v[232:233], v[126:127] op_sel:[0,1,0]
	v_pk_fma_f32 v[128:129], v[194:195], v[232:233], v[128:129] op_sel:[0,1,0]
	v_pk_fma_f32 v[130:131], v[196:197], v[232:233], v[130:131] op_sel:[0,1,0]
	v_pk_fma_f32 v[132:133], v[198:199], v[232:233], v[132:133] op_sel:[0,1,0]
	v_pk_fma_f32 v[134:135], v[200:201], v[232:233], v[134:135] op_sel:[0,1,0]
	v_pk_fma_f32 v[136:137], v[202:203], v[232:233], v[136:137] op_sel:[0,1,0]
	v_pk_fma_f32 v[148:149], v[204:205], v[232:233], v[148:149] op_sel:[0,1,0]
	v_pk_fma_f32 v[150:151], v[206:207], v[232:233], v[150:151] op_sel:[0,1,0]
	v_pk_fma_f32 v[152:153], v[208:209], v[232:233], v[152:153] op_sel:[0,1,0]
	v_pk_fma_f32 v[154:155], v[210:211], v[232:233], v[154:155] op_sel:[0,1,0]
	v_pk_fma_f32 v[156:157], v[212:213], v[232:233], v[156:157] op_sel:[0,1,0]
	v_pk_fma_f32 v[158:159], v[166:167], v[232:233], v[158:159] op_sel:[0,1,0]
	v_pk_fma_f32 v[160:161], v[168:169], v[232:233], v[160:161] op_sel:[0,1,0]
	v_pk_fma_f32 v[162:163], v[170:171], v[232:233], v[162:163] op_sel:[0,1,0]
	v_pk_fma_f32 v[164:165], v[172:173], v[232:233], v[164:165] op_sel:[0,1,0]
	ds_read2st64_b32 v[232:233], v231 offset0:160 offset1:164
	s_waitcnt lgkmcnt(4)
	v_pk_fma_f32 v[126:127], v[72:73], v[234:235], v[126:127] op_sel_hi:[1,0,1]
	v_pk_fma_f32 v[128:129], v[74:75], v[234:235], v[128:129] op_sel_hi:[1,0,1]
	v_pk_fma_f32 v[130:131], v[76:77], v[234:235], v[130:131] op_sel_hi:[1,0,1]
	v_pk_fma_f32 v[132:133], v[78:79], v[234:235], v[132:133] op_sel_hi:[1,0,1]
	v_pk_fma_f32 v[134:135], v[80:81], v[234:235], v[134:135] op_sel_hi:[1,0,1]
	v_pk_fma_f32 v[136:137], v[82:83], v[234:235], v[136:137] op_sel_hi:[1,0,1]
	v_pk_fma_f32 v[148:149], v[84:85], v[234:235], v[148:149] op_sel_hi:[1,0,1]
	v_pk_fma_f32 v[150:151], v[86:87], v[234:235], v[150:151] op_sel_hi:[1,0,1]
	v_pk_fma_f32 v[152:153], v[88:89], v[234:235], v[152:153] op_sel_hi:[1,0,1]
	v_pk_fma_f32 v[154:155], v[90:91], v[234:235], v[154:155] op_sel_hi:[1,0,1]
	v_pk_fma_f32 v[156:157], v[92:93], v[234:235], v[156:157] op_sel_hi:[1,0,1]
	v_pk_fma_f32 v[158:159], v[94:95], v[234:235], v[158:159] op_sel_hi:[1,0,1]
	v_pk_fma_f32 v[160:161], v[96:97], v[234:235], v[160:161] op_sel_hi:[1,0,1]
	v_pk_fma_f32 v[162:163], v[98:99], v[234:235], v[162:163] op_sel_hi:[1,0,1]
	v_pk_fma_f32 v[164:165], v[100:101], v[234:235], v[164:165] op_sel_hi:[1,0,1]
	v_fmac_f32_e32 v127, v72, v235
	v_pk_fma_f32 v[128:129], v[192:193], v[234:235], v[128:129] op_sel:[0,1,0]
	v_pk_fma_f32 v[130:131], v[194:195], v[234:235], v[130:131] op_sel:[0,1,0]
	v_pk_fma_f32 v[132:133], v[196:197], v[234:235], v[132:133] op_sel:[0,1,0]
	v_pk_fma_f32 v[134:135], v[198:199], v[234:235], v[134:135] op_sel:[0,1,0]
	v_pk_fma_f32 v[136:137], v[200:201], v[234:235], v[136:137] op_sel:[0,1,0]
	v_pk_fma_f32 v[148:149], v[202:203], v[234:235], v[148:149] op_sel:[0,1,0]
	v_pk_fma_f32 v[150:151], v[204:205], v[234:235], v[150:151] op_sel:[0,1,0]
	v_pk_fma_f32 v[152:153], v[206:207], v[234:235], v[152:153] op_sel:[0,1,0]
	v_pk_fma_f32 v[154:155], v[208:209], v[234:235], v[154:155] op_sel:[0,1,0]
	v_pk_fma_f32 v[156:157], v[210:211], v[234:235], v[156:157] op_sel:[0,1,0]
	v_pk_fma_f32 v[158:159], v[212:213], v[234:235], v[158:159] op_sel:[0,1,0]
	v_pk_fma_f32 v[160:161], v[166:167], v[234:235], v[160:161] op_sel:[0,1,0]
	v_pk_fma_f32 v[162:163], v[168:169], v[234:235], v[162:163] op_sel:[0,1,0]
	v_pk_fma_f32 v[164:165], v[170:171], v[234:235], v[164:165] op_sel:[0,1,0]
	ds_read2st64_b32 v[234:235], v231 offset0:168 offset1:172
	s_waitcnt lgkmcnt(4)
; #define LAS __attribute__((address_space(3)))
;     static __device__ __forceinline__ void run(float (&acc)[32], const float (&wv)[31], const LAS float* U, int rb, int cch) {
;         const float uv = U[ring94(ring94(rb + S)) * 256 + cch];
; #pragma unroll
;         for (int o = 0; o < 32; ++o) { constexpr int dummy = 0; const int kk = S - o + dummy; if (kk >= 0 && kk <= 30) acc[o] += wv[kk] * uv; }
	v_pk_fma_f32 v[128:129], v[72:73], v[236:237], v[128:129] op_sel_hi:[1,0,1]
	v_pk_fma_f32 v[130:131], v[74:75], v[236:237], v[130:131] op_sel_hi:[1,0,1]
	v_pk_fma_f32 v[132:133], v[76:77], v[236:237], v[132:133] op_sel_hi:[1,0,1]
	v_pk_fma_f32 v[134:135], v[78:79], v[236:237], v[134:135] op_sel_hi:[1,0,1]
	v_pk_fma_f32 v[136:137], v[80:81], v[236:237], v[136:137] op_sel_hi:[1,0,1]
	v_pk_fma_f32 v[148:149], v[82:83], v[236:237], v[148:149] op_sel_hi:[1,0,1]
	v_pk_fma_f32 v[150:151], v[84:85], v[236:237], v[150:151] op_sel_hi:[1,0,1]
	v_pk_fma_f32 v[152:153], v[86:87], v[236:237], v[152:153] op_sel_hi:[1,0,1]
	v_pk_fma_f32 v[154:155], v[88:89], v[236:237], v[154:155] op_sel_hi:[1,0,1]
	v_pk_fma_f32 v[156:157], v[90:91], v[236:237], v[156:157] op_sel_hi:[1,0,1]
	v_pk_fma_f32 v[158:159], v[92:93], v[236:237], v[158:159] op_sel_hi:[1,0,1]
	v_pk_fma_f32 v[160:161], v[94:95], v[236:237], v[160:161] op_sel_hi:[1,0,1]
	v_pk_fma_f32 v[162:163], v[96:97], v[236:237], v[162:163] op_sel_hi:[1,0,1]
	v_pk_fma_f32 v[164:165], v[98:99], v[236:237], v[164:165] op_sel_hi:[1,0,1]
	v_fmac_f32_e32 v129, v72, v237
	v_pk_fma_f32 v[130:131], v[192:193], v[236:237], v[130:131] op_sel:[0,1,0]
	v_pk_fma_f32 v[132:133], v[194:195], v[236:237], v[132:133] op_sel:[0,1,0]
	v_pk_fma_f32 v[134:135], v[196:197], v[236:237], v[134:135] op_sel:[0,1,0]
	v_pk_fma_f32 v[136:137], v[198:199], v[236:237], v[136:137] op_sel:[0,1,0]
	v_pk_fma_f32 v[148:149], v[200:201], v[236:237], v[148:149] op_sel:[0,1,0]
	v_pk_fma_f32 v[150:151], v[202:203], v[236:237], v[150:151] op_sel:[0,1,0]
	v_pk_fma_f32 v[152:153], v[204:205], v[236:237], v[152:153] op_sel:[0,1,0]
	v_pk_fma_f32 v[154:155], v[206:207], v[236:237], v[154:155] op_sel:[0,1,0]
	v_pk_fma_f32 v[156:157], v[208:209], v[236:237], v[156:157] op_sel:[0,1,0]
	v_pk_fma_f32 v[158:159], v[210:211], v[236:237], v[158:159] op_sel:[0,1,0]
	v_pk_fma_f32 v[160:161], v[212:213], v[236:237], v[160:161] op_sel:[0,1,0]
	v_pk_fma_f32 v[162:163], v[166:167], v[236:237], v[162:163] op_sel:[0,1,0]
	v_pk_fma_f32 v[164:165], v[168:169], v[236:237], v[164:165] op_sel:[0,1,0]
	ds_read2st64_b32 v[236:237], v231 offset0:176 offset1:180
	s_waitcnt lgkmcnt(4)
	v_pk_fma_f32 v[130:131], v[72:73], v[238:239], v[130:131] op_sel_hi:[1,0,1]
	v_pk_fma_f32 v[132:133], v[74:75], v[238:239], v[132:133] op_sel_hi:[1,0,1]
	v_pk_fma_f32 v[134:135], v[76:77], v[238:239], v[134:135] op_sel_hi:[1,0,1]
	v_pk_fma_f32 v[136:137], v[78:79], v[238:239], v[136:137] op_sel_hi:[1,0,1]
	v_pk_fma_f32 v[148:149], v[80:81], v[238:239], v[148:149] op_sel_hi:[1,0,1]
	v_pk_fma_f32 v[150:151], v[82:83], v[238:239], v[150:151] op_sel_hi:[1,0,1]
	v_pk_fma_f32 v[152:153], v[84:85], v[238:239], v[152:153] op_sel_hi:[1,0,1]
	v_pk_fma_f32 v[154:155], v[86:87], v[238:239], v[154:155] op_sel_hi:[1,0,1]
	v_pk_fma_f32 v[156:157], v[88:89], v[238:239], v[156:157] op_sel_hi:[1,0,1]
	v_pk_fma_f32 v[158:159], v[90:91], v[238:239], v[158:159] op_sel_hi:[1,0,1]
	v_pk_fma_f32 v[160:161], v[92:93], v[238:239], v[160:161] op_sel_hi:[1,0,1]
	v_pk_fma_f32 v[162:163], v[94:95], v[238:239], v[162:163] op_sel_hi:[1,0,1]
	v_pk_fma_f32 v[164:165], v[96:97], v[238:239], v[164:165] op_sel_hi:[1,0,1]
	v_fmac_f32_e32 v131, v72, v239
	v_pk_fma_f32 v[132:133], v[192:193], v[238:239], v[132:133] op_sel:[0,1,0]
	v_pk_fma_f32 v[134:135], v[194:195], v[238:239], v[134:135] op_sel:[0,1,0]
	v_pk_fma_f32 v[136:137], v[196:197], v[238:239], v[136:137] op_sel:[0,1,0]
	v_pk_fma_f32 v[148:149], v[198:199], v[238:239], v[148:149] op_sel:[0,1,0]
	v_pk_fma_f32 v[150:151], v[200:201], v[238:239], v[150:151] op_sel:[0,1,0]
	v_pk_fma_f32 v[152:153], v[202:203], v[238:239], v[152:153] op_sel:[0,1,0]
	v_pk_fma_f32 v[154:155], v[204:205], v[238:239], v[154:155] op_sel:[0,1,0]
	v_pk_fma_f32 v[156:157], v[206:207], v[238:239], v[156:157] op_sel:[0,1,0]
	v_pk_fma_f32 v[158:159], v[208:209], v[238:239], v[158:159] op_sel:[0,1,0]
	v_pk_fma_f32 v[160:161], v[210:211], v[238:239], v[160:161] op_sel:[0,1,0]
	v_pk_fma_f32 v[162:163], v[212:213], v[238:239], v[162:163] op_sel:[0,1,0]
	v_pk_fma_f32 v[164:165], v[166:167], v[238:239], v[164:165] op_sel:[0,1,0]
	ds_read2st64_b32 v[238:239], v231 offset0:184 offset1:188
	s_waitcnt lgkmcnt(4)
	v_pk_fma_f32 v[132:133], v[72:73], v[240:241], v[132:133] op_sel_hi:[1,0,1]
	v_pk_fma_f32 v[134:135], v[74:75], v[240:241], v[134:135] op_sel_hi:[1,0,1]
	v_pk_fma_f32 v[136:137], v[76:77], v[240:241], v[136:137] op_sel_hi:[1,0,1]
	v_pk_fma_f32 v[148:149], v[78:79], v[240:241], v[148:149] op_sel_hi:[1,0,1]
	v_pk_fma_f32 v[150:151], v[80:81], v[240:241], v[150:151] op_sel_hi:[1,0,1]
	v_pk_fma_f32 v[152:153], v[82:83], v[240:241], v[152:153] op_sel_hi:[1,0,1]
	v_pk_fma_f32 v[154:155], v[84:85], v[240:241], v[154:155] op_sel_hi:[1,0,1]
	v_pk_fma_f32 v[156:157], v[86:87], v[240:241], v[156:157] op_sel_hi:[1,0,1]
	v_pk_fma_f32 v[158:159], v[88:89], v[240:241], v[158:159] op_sel_hi:[1,0,1]
	v_pk_fma_f32 v[160:161], v[90:91], v[240:241], v[160:161] op_sel_hi:[1,0,1]
	v_pk_fma_f32 v[162:163], v[92:93], v[240:241], v[162:163] op_sel_hi:[1,0,1]
	v_pk_fma_f32 v[164:165], v[94:95], v[240:241], v[164:165] op_sel_hi:[1,0,1]
	v_fmac_f32_e32 v133, v72, v241
	v_pk_fma_f32 v[134:135], v[192:193], v[240:241], v[134:135] op_sel:[0,1,0]
	v_pk_fma_f32 v[136:137], v[194:195], v[240:241], v[136:137] op_sel:[0,1,0]
	v_pk_fma_f32 v[148:149], v[196:197], v[240:241], v[148:149] op_sel:[0,1,0]
	v_pk_fma_f32 v[150:151], v[198:199], v[240:241], v[150:151] op_sel:[0,1,0]
	v_pk_fma_f32 v[152:153], v[200:201], v[240:241], v[152:153] op_sel:[0,1,0]
	v_pk_fma_f32 v[154:155], v[202:203], v[240:241], v[154:155] op_sel:[0,1,0]
	v_pk_fma_f32 v[156:157], v[204:205], v[240:241], v[156:157] op_sel:[0,1,0]
	v_pk_fma_f32 v[158:159], v[206:207], v[240:241], v[158:159] op_sel:[0,1,0]
	v_pk_fma_f32 v[160:161], v[208:209], v[240:241], v[160:161] op_sel:[0,1,0]
	v_pk_fma_f32 v[162:163], v[210:211], v[240:241], v[162:163] op_sel:[0,1,0]
	v_pk_fma_f32 v[164:165], v[212:213], v[240:241], v[164:165] op_sel:[0,1,0]
	ds_read2st64_b32 v[240:241], v231 offset0:192 offset1:196
	s_waitcnt lgkmcnt(4)
; #define LAS __attribute__((address_space(3)))
;     static __device__ __forceinline__ void run(float (&acc)[32], const float (&wv)[31], const LAS float* U, int rb, int cch) {
;         const float uv = U[ring94(ring94(rb + S)) * 256 + cch];
; #pragma unroll
;         for (int o = 0; o < 32; ++o) { constexpr int dummy = 0; const int kk = S - o + dummy; if (kk >= 0 && kk <= 30) acc[o] += wv[kk] * uv; }
	v_pk_fma_f32 v[134:135], v[72:73], v[232:233], v[134:135] op_sel_hi:[1,0,1]
	v_pk_fma_f32 v[136:137], v[74:75], v[232:233], v[136:137] op_sel_hi:[1,0,1]
	v_pk_fma_f32 v[148:149], v[76:77], v[232:233], v[148:149] op_sel_hi:[1,0,1]
	v_pk_fma_f32 v[150:151], v[78:79], v[232:233], v[150:151] op_sel_hi:[1,0,1]
	v_pk_fma_f32 v[152:153], v[80:81], v[232:233], v[152:153] op_sel_hi:[1,0,1]
	v_pk_fma_f32 v[154:155], v[82:83], v[232:233], v[154:155] op_sel_hi:[1,0,1]
	v_pk_fma_f32 v[156:157], v[84:85], v[232:233], v[156:157] op_sel_hi:[1,0,1]
	v_pk_fma_f32 v[158:159], v[86:87], v[232:233], v[158:159] op_sel_hi:[1,0,1]
	v_pk_fma_f32 v[160:161], v[88:89], v[232:233], v[160:161] op_sel_hi:[1,0,1]
	v_pk_fma_f32 v[162:163], v[90:91], v[232:233], v[162:163] op_sel_hi:[1,0,1]
	v_pk_fma_f32 v[164:165], v[92:93], v[232:233], v[164:165] op_sel_hi:[1,0,1]
	v_fmac_f32_e32 v135, v72, v233
	v_pk_fma_f32 v[136:137], v[192:193], v[232:233], v[136:137] op_sel:[0,1,0]
	v_pk_fma_f32 v[148:149], v[194:195], v[232:233], v[148:149] op_sel:[0,1,0]
	v_pk_fma_f32 v[150:151], v[196:197], v[232:233], v[150:151] op_sel:[0,1,0]
	v_pk_fma_f32 v[152:153], v[198:199], v[232:233], v[152:153] op_sel:[0,1,0]
	v_pk_fma_f32 v[154:155], v[200:201], v[232:233], v[154:155] op_sel:[0,1,0]
	v_pk_fma_f32 v[156:157], v[202:203], v[232:233], v[156:157] op_sel:[0,1,0]
	v_pk_fma_f32 v[158:159], v[204:205], v[232:233], v[158:159] op_sel:[0,1,0]
	v_pk_fma_f32 v[160:161], v[206:207], v[232:233], v[160:161] op_sel:[0,1,0]
	v_pk_fma_f32 v[162:163], v[208:209], v[232:233], v[162:163] op_sel:[0,1,0]
	v_pk_fma_f32 v[164:165], v[210:211], v[232:233], v[164:165] op_sel:[0,1,0]
	ds_read2st64_b32 v[232:233], v231 offset0:200 offset1:204
	s_waitcnt lgkmcnt(4)
	v_pk_fma_f32 v[136:137], v[72:73], v[234:235], v[136:137] op_sel_hi:[1,0,1]
	v_pk_fma_f32 v[148:149], v[74:75], v[234:235], v[148:149] op_sel_hi:[1,0,1]
	v_pk_fma_f32 v[150:151], v[76:77], v[234:235], v[150:151] op_sel_hi:[1,0,1]
	v_pk_fma_f32 v[152:153], v[78:79], v[234:235], v[152:153] op_sel_hi:[1,0,1]
	v_pk_fma_f32 v[154:155], v[80:81], v[234:235], v[154:155] op_sel_hi:[1,0,1]
	v_pk_fma_f32 v[156:157], v[82:83], v[234:235], v[156:157] op_sel_hi:[1,0,1]
	v_pk_fma_f32 v[158:159], v[84:85], v[234:235], v[158:159] op_sel_hi:[1,0,1]
	v_pk_fma_f32 v[160:161], v[86:87], v[234:235], v[160:161] op_sel_hi:[1,0,1]
	v_pk_fma_f32 v[162:163], v[88:89], v[234:235], v[162:163] op_sel_hi:[1,0,1]
	v_pk_fma_f32 v[164:165], v[90:91], v[234:235], v[164:165] op_sel_hi:[1,0,1]
	v_fmac_f32_e32 v137, v72, v235
	v_pk_fma_f32 v[148:149], v[192:193], v[234:235], v[148:149] op_sel:[0,1,0]
	v_pk_fma_f32 v[150:151], v[194:195], v[234:235], v[150:151] op_sel:[0,1,0]
	v_pk_fma_f32 v[152:153], v[196:197], v[234:235], v[152:153] op_sel:[0,1,0]
	v_pk_fma_f32 v[154:155], v[198:199], v[234:235], v[154:155] op_sel:[0,1,0]
	v_pk_fma_f32 v[156:157], v[200:201], v[234:235], v[156:157] op_sel:[0,1,0]
	v_pk_fma_f32 v[158:159], v[202:203], v[234:235], v[158:159] op_sel:[0,1,0]
	v_pk_fma_f32 v[160:161], v[204:205], v[234:235], v[160:161] op_sel:[0,1,0]
	v_pk_fma_f32 v[162:163], v[206:207], v[234:235], v[162:163] op_sel:[0,1,0]
	v_pk_fma_f32 v[164:165], v[208:209], v[234:235], v[164:165] op_sel:[0,1,0]
	ds_read2st64_b32 v[234:235], v231 offset0:208 offset1:212
	s_waitcnt lgkmcnt(4)
	v_pk_fma_f32 v[148:149], v[72:73], v[236:237], v[148:149] op_sel_hi:[1,0,1]
	v_pk_fma_f32 v[150:151], v[74:75], v[236:237], v[150:151] op_sel_hi:[1,0,1]
	v_pk_fma_f32 v[152:153], v[76:77], v[236:237], v[152:153] op_sel_hi:[1,0,1]
	v_pk_fma_f32 v[154:155], v[78:79], v[236:237], v[154:155] op_sel_hi:[1,0,1]
	v_pk_fma_f32 v[156:157], v[80:81], v[236:237], v[156:157] op_sel_hi:[1,0,1]
	v_pk_fma_f32 v[158:159], v[82:83], v[236:237], v[158:159] op_sel_hi:[1,0,1]
	v_pk_fma_f32 v[160:161], v[84:85], v[236:237], v[160:161] op_sel_hi:[1,0,1]
	v_pk_fma_f32 v[162:163], v[86:87], v[236:237], v[162:163] op_sel_hi:[1,0,1]
	v_pk_fma_f32 v[164:165], v[88:89], v[236:237], v[164:165] op_sel_hi:[1,0,1]
	v_fmac_f32_e32 v149, v72, v237
	v_pk_fma_f32 v[150:151], v[192:193], v[236:237], v[150:151] op_sel:[0,1,0]
	v_pk_fma_f32 v[152:153], v[194:195], v[236:237], v[152:153] op_sel:[0,1,0]
	v_pk_fma_f32 v[154:155], v[196:197], v[236:237], v[154:155] op_sel:[0,1,0]
	v_pk_fma_f32 v[156:157], v[198:199], v[236:237], v[156:157] op_sel:[0,1,0]
	v_pk_fma_f32 v[158:159], v[200:201], v[236:237], v[158:159] op_sel:[0,1,0]
	v_pk_fma_f32 v[160:161], v[202:203], v[236:237], v[160:161] op_sel:[0,1,0]
	v_pk_fma_f32 v[162:163], v[204:205], v[236:237], v[162:163] op_sel:[0,1,0]
	v_pk_fma_f32 v[164:165], v[206:207], v[236:237], v[164:165] op_sel:[0,1,0]
	ds_read2st64_b32 v[236:237], v231 offset0:216 offset1:220
	s_waitcnt lgkmcnt(4)
	v_pk_fma_f32 v[150:151], v[72:73], v[238:239], v[150:151] op_sel_hi:[1,0,1]
	v_pk_fma_f32 v[152:153], v[74:75], v[238:239], v[152:153] op_sel_hi:[1,0,1]
	v_pk_fma_f32 v[154:155], v[76:77], v[238:239], v[154:155] op_sel_hi:[1,0,1]
	v_pk_fma_f32 v[156:157], v[78:79], v[238:239], v[156:157] op_sel_hi:[1,0,1]
	v_pk_fma_f32 v[158:159], v[80:81], v[238:239], v[158:159] op_sel_hi:[1,0,1]
	v_pk_fma_f32 v[160:161], v[82:83], v[238:239], v[160:161] op_sel_hi:[1,0,1]
	v_pk_fma_f32 v[162:163], v[84:85], v[238:239], v[162:163] op_sel_hi:[1,0,1]
	v_pk_fma_f32 v[164:165], v[86:87], v[238:239], v[164:165] op_sel_hi:[1,0,1]
	v_fmac_f32_e32 v151, v72, v239
	v_pk_fma_f32 v[152:153], v[192:193], v[238:239], v[152:153] op_sel:[0,1,0]
	v_pk_fma_f32 v[154:155], v[194:195], v[238:239], v[154:155] op_sel:[0,1,0]
	v_pk_fma_f32 v[156:157], v[196:197], v[238:239], v[156:157] op_sel:[0,1,0]
	v_pk_fma_f32 v[158:159], v[198:199], v[238:239], v[158:159] op_sel:[0,1,0]
	v_pk_fma_f32 v[160:161], v[200:201], v[238:239], v[160:161] op_sel:[0,1,0]
	v_pk_fma_f32 v[162:163], v[202:203], v[238:239], v[162:163] op_sel:[0,1,0]
	v_pk_fma_f32 v[164:165], v[204:205], v[238:239], v[164:165] op_sel:[0,1,0]
	ds_read2st64_b32 v[238:239], v231 offset0:224 offset1:228
	s_waitcnt lgkmcnt(4)
; #define LAS __attribute__((address_space(3)))
;     static __device__ __forceinline__ void run(float (&acc)[32], const float (&wv)[31], const LAS float* U, int rb, int cch) {
;         const float uv = U[ring94(ring94(rb + S)) * 256 + cch];
; #pragma unroll
;         for (int o = 0; o < 32; ++o) { constexpr int dummy = 0; const int kk = S - o + dummy; if (kk >= 0 && kk <= 30) acc[o] += wv[kk] * uv; }
; __device__ __forceinline__ void conv_loop(unsigned char* ws_, const float* const* in_, int l_, LAS unsigned char* lds, int tid, int bid, int G) {
;     ...
;             __syncthreads();
; #pragma unroll
;             for (int o = 0; o < 32; ++o) U[ring94(ring94(rb + o)) * 256 + cch] = acc[o];
	v_pk_fma_f32 v[152:153], v[72:73], v[240:241], v[152:153] op_sel_hi:[1,0,1]
	v_pk_fma_f32 v[154:155], v[74:75], v[240:241], v[154:155] op_sel_hi:[1,0,1]
	v_pk_fma_f32 v[156:157], v[76:77], v[240:241], v[156:157] op_sel_hi:[1,0,1]
	v_pk_fma_f32 v[158:159], v[78:79], v[240:241], v[158:159] op_sel_hi:[1,0,1]
	v_pk_fma_f32 v[160:161], v[80:81], v[240:241], v[160:161] op_sel_hi:[1,0,1]
	v_pk_fma_f32 v[162:163], v[82:83], v[240:241], v[162:163] op_sel_hi:[1,0,1]
	v_pk_fma_f32 v[164:165], v[84:85], v[240:241], v[164:165] op_sel_hi:[1,0,1]
	v_fmac_f32_e32 v153, v72, v241
	v_pk_fma_f32 v[154:155], v[192:193], v[240:241], v[154:155] op_sel:[0,1,0]
	v_pk_fma_f32 v[156:157], v[194:195], v[240:241], v[156:157] op_sel:[0,1,0]
	v_pk_fma_f32 v[158:159], v[196:197], v[240:241], v[158:159] op_sel:[0,1,0]
	v_pk_fma_f32 v[160:161], v[198:199], v[240:241], v[160:161] op_sel:[0,1,0]
	v_pk_fma_f32 v[162:163], v[200:201], v[240:241], v[162:163] op_sel:[0,1,0]
	v_pk_fma_f32 v[164:165], v[202:203], v[240:241], v[164:165] op_sel:[0,1,0]
	ds_read2st64_b32 v[240:241], v231 offset0:232 offset1:236
	s_waitcnt lgkmcnt(4)
	v_pk_fma_f32 v[154:155], v[72:73], v[232:233], v[154:155] op_sel_hi:[1,0,1]
	v_pk_fma_f32 v[156:157], v[74:75], v[232:233], v[156:157] op_sel_hi:[1,0,1]
	v_pk_fma_f32 v[158:159], v[76:77], v[232:233], v[158:159] op_sel_hi:[1,0,1]
	v_pk_fma_f32 v[160:161], v[78:79], v[232:233], v[160:161] op_sel_hi:[1,0,1]
	v_pk_fma_f32 v[162:163], v[80:81], v[232:233], v[162:163] op_sel_hi:[1,0,1]
	v_pk_fma_f32 v[164:165], v[82:83], v[232:233], v[164:165] op_sel_hi:[1,0,1]
	v_fmac_f32_e32 v155, v72, v233
	v_pk_fma_f32 v[156:157], v[192:193], v[232:233], v[156:157] op_sel:[0,1,0]
	v_pk_fma_f32 v[158:159], v[194:195], v[232:233], v[158:159] op_sel:[0,1,0]
	v_pk_fma_f32 v[160:161], v[196:197], v[232:233], v[160:161] op_sel:[0,1,0]
	v_pk_fma_f32 v[162:163], v[198:199], v[232:233], v[162:163] op_sel:[0,1,0]
	v_pk_fma_f32 v[164:165], v[200:201], v[232:233], v[164:165] op_sel:[0,1,0]
	ds_read2st64_b32 v[232:233], v231 offset0:240 offset1:244
	s_waitcnt lgkmcnt(4)
	v_pk_fma_f32 v[156:157], v[72:73], v[234:235], v[156:157] op_sel_hi:[1,0,1]
	v_pk_fma_f32 v[158:159], v[74:75], v[234:235], v[158:159] op_sel_hi:[1,0,1]
	v_pk_fma_f32 v[160:161], v[76:77], v[234:235], v[160:161] op_sel_hi:[1,0,1]
	v_pk_fma_f32 v[162:163], v[78:79], v[234:235], v[162:163] op_sel_hi:[1,0,1]
	v_pk_fma_f32 v[164:165], v[80:81], v[234:235], v[164:165] op_sel_hi:[1,0,1]
	v_fmac_f32_e32 v157, v72, v235
	v_pk_fma_f32 v[158:159], v[192:193], v[234:235], v[158:159] op_sel:[0,1,0]
	v_pk_fma_f32 v[160:161], v[194:195], v[234:235], v[160:161] op_sel:[0,1,0]
	v_pk_fma_f32 v[162:163], v[196:197], v[234:235], v[162:163] op_sel:[0,1,0]
	v_pk_fma_f32 v[164:165], v[198:199], v[234:235], v[164:165] op_sel:[0,1,0]
	s_waitcnt lgkmcnt(3)
	v_pk_fma_f32 v[158:159], v[72:73], v[236:237], v[158:159] op_sel_hi:[1,0,1]
	v_pk_fma_f32 v[160:161], v[74:75], v[236:237], v[160:161] op_sel_hi:[1,0,1]
	v_pk_fma_f32 v[162:163], v[76:77], v[236:237], v[162:163] op_sel_hi:[1,0,1]
	v_pk_fma_f32 v[164:165], v[78:79], v[236:237], v[164:165] op_sel_hi:[1,0,1]
	v_fmac_f32_e32 v159, v72, v237
	v_pk_fma_f32 v[160:161], v[192:193], v[236:237], v[160:161] op_sel:[0,1,0]
	v_pk_fma_f32 v[162:163], v[194:195], v[236:237], v[162:163] op_sel:[0,1,0]
	v_pk_fma_f32 v[164:165], v[196:197], v[236:237], v[164:165] op_sel:[0,1,0]
	s_waitcnt lgkmcnt(2)
	v_pk_fma_f32 v[160:161], v[72:73], v[238:239], v[160:161] op_sel_hi:[1,0,1]
	v_pk_fma_f32 v[162:163], v[74:75], v[238:239], v[162:163] op_sel_hi:[1,0,1]
	v_pk_fma_f32 v[164:165], v[76:77], v[238:239], v[164:165] op_sel_hi:[1,0,1]
	v_fmac_f32_e32 v161, v72, v239
	v_pk_fma_f32 v[162:163], v[192:193], v[238:239], v[162:163] op_sel:[0,1,0]
	v_pk_fma_f32 v[164:165], v[194:195], v[238:239], v[164:165] op_sel:[0,1,0]
	s_waitcnt lgkmcnt(1)
	v_pk_fma_f32 v[162:163], v[72:73], v[240:241], v[162:163] op_sel_hi:[1,0,1]
	v_pk_fma_f32 v[164:165], v[74:75], v[240:241], v[164:165] op_sel_hi:[1,0,1]
	v_fmac_f32_e32 v163, v72, v241
	v_pk_fma_f32 v[164:165], v[192:193], v[240:241], v[164:165] op_sel:[0,1,0]
	s_waitcnt lgkmcnt(0)
	v_pk_fma_f32 v[164:165], v[72:73], v[232:233], v[164:165] op_sel_hi:[1,0,1]
	v_fmac_f32_e32 v165, v72, v233
	ds_read_b32 v214, v230 offset:0
	ds_read_b32 v215, v230 offset:1024
	ds_read_b32 v216, v230 offset:2048
	ds_read_b32 v217, v230 offset:3072
	ds_read_b32 v218, v230 offset:4096
	ds_read_b32 v219, v230 offset:5120
	ds_read_b32 v220, v230 offset:6144
	ds_read_b32 v221, v230 offset:7168
	ds_read_b32 v222, v230 offset:8192
	ds_read_b32 v223, v230 offset:9216
	ds_read_b32 v224, v230 offset:10240
	ds_read_b32 v225, v230 offset:11264
	ds_read_b32 v226, v230 offset:12288
	ds_read_b32 v227, v230 offset:13312
	ds_read_b32 v228, v230 offset:14336
	s_barrier
	ds_write_b32 v231, v124 offset:0
	ds_write_b32 v231, v125 offset:1024
	ds_write_b32 v231, v126 offset:2048
	ds_write_b32 v231, v127 offset:3072
	ds_write_b32 v231, v128 offset:4096
	ds_write_b32 v231, v129 offset:5120
	ds_write_b32 v231, v130 offset:6144
	ds_write_b32 v231, v131 offset:7168
	ds_write_b32 v231, v132 offset:8192
	ds_write_b32 v231, v133 offset:9216
	ds_write_b32 v231, v134 offset:10240
	ds_write_b32 v231, v135 offset:11264
	ds_write_b32 v231, v136 offset:12288
	ds_write_b32 v231, v137 offset:13312
	ds_write_b32 v231, v148 offset:14336
	ds_write_b32 v231, v149 offset:15360
	ds_write_b32 v231, v150 offset:16384
	ds_write_b32 v231, v151 offset:17408
	ds_write_b32 v231, v152 offset:18432
	ds_write_b32 v231, v153 offset:19456
	ds_write_b32 v231, v154 offset:20480
	ds_write_b32 v231, v155 offset:21504
	ds_write_b32 v231, v156 offset:22528
	ds_write_b32 v231, v157 offset:23552
	ds_write_b32 v231, v158 offset:24576
	ds_write_b32 v231, v159 offset:25600
	ds_write_b32 v231, v160 offset:26624
	ds_write_b32 v231, v161 offset:27648
	ds_write_b32 v231, v162 offset:28672
	ds_write_b32 v231, v163 offset:29696
	ds_write_b32 v231, v164 offset:30720
	ds_write_b32 v231, v165 offset:31744
	v_add_u32_e32 v63, s26, v52
	v_cmp_lt_i32_e32 vcc, s91, v63
	v_lshlrev_b32_e32 v63, 10, v63
	v_add_u32_e32 v70, 0xfffe8800, v63
	v_cndmask_b32_e32 v63, v63, v70, vcc
	v_add_u32_e32 v63, v105, v63
	s_waitcnt lgkmcnt(0)
	s_barrier
; #define LAS __attribute__((address_space(3)))
; __device__ __forceinline__ void conv_loop(unsigned char* ws_, const float* const* in_, int l_, LAS unsigned char* lds, int tid, int bid, int G) {
;     ...
;             for (int i = 0; i < 8; ++i) { const int tok = 8 * w + i; f32x4 v = *(LAS f32x4*)(U + ring94(base + tok) * 256 + 4 * lane);
;                 const float mean = wave_sum((v[0] + v[1]) + (v[2] + v[3])) * (1.0f / 256.0f);
	v_lshl_add_u32 v188, v52, 10, v105
	ds_read_b128 v[124:127], v188 offset:0
	ds_read_b128 v[128:131], v188 offset:1024
	ds_read_b128 v[132:135], v188 offset:2048
	ds_read_b128 v[148:151], v188 offset:3072
	ds_read_b128 v[152:155], v188 offset:4096
	ds_read_b128 v[156:159], v188 offset:5120
	ds_read_b128 v[160:163], v188 offset:6144
	ds_read_b128 v[164:167], v188 offset:7168
	s_mov_b32 s76, 0x1000
	s_mov_b32 s77, 0
	s_mov_b32 s78, 0xbfb8aa3b
	s_mov_b32 s80, 1.0
	v_lshl_add_u64 v[206:207], v[48:49], 0, s[42:43]
	v_lshl_add_u64 v[48:49], v[48:49], 0, s[74:75]
	v_lshl_add_u64 v[44:45], v[44:45], 0, s[74:75]
	v_lshl_add_u64 v[42:43], v[42:43], 0, s[74:75]
	v_lshl_add_u64 v[208:209], v[206:207], 0, s[76:77]
	v_lshl_add_u64 v[210:211], v[208:209], 0, s[76:77]
	v_lshl_add_u64 v[212:213], v[210:211], 0, s[76:77]
	s_add_i32 s27, s27, -1
	s_waitcnt lgkmcnt(7)
	v_add_f32_e32 v168, v125, v124
	v_add_f32_e32 v194, v126, v127
	s_waitcnt lgkmcnt(6)
	v_add_f32_e32 v169, v129, v128
	v_add_f32_e32 v195, v130, v131
	s_waitcnt lgkmcnt(5)
	v_add_f32_e32 v170, v133, v132
	v_add_f32_e32 v196, v134, v135
	s_waitcnt lgkmcnt(4)
	v_add_f32_e32 v171, v149, v148
	v_add_f32_e32 v197, v150, v151
	s_waitcnt lgkmcnt(3)
	v_add_f32_e32 v172, v153, v152
	v_add_f32_e32 v198, v154, v155
	s_waitcnt lgkmcnt(2)
	v_add_f32_e32 v173, v157, v156
	v_add_f32_e32 v199, v158, v159
	s_waitcnt lgkmcnt(1)
	v_add_f32_e32 v192, v161, v160
	v_add_f32_e32 v200, v162, v163
	s_waitcnt lgkmcnt(0)
	v_add_f32_e32 v193, v165, v164
	v_add_f32_e32 v201, v166, v167
	v_add_f32_e32 v168, v168, v194
	v_add_f32_e32 v169, v169, v195
	v_add_f32_e32 v170, v170, v196
	v_add_f32_e32 v171, v171, v197
	v_add_f32_e32 v172, v172, v198
	v_add_f32_e32 v173, v173, v199
	v_add_f32_e32 v192, v192, v200
	v_add_f32_e32 v193, v193, v201
	v_add_f32_dpp v168, v168, v168 quad_perm:[1,0,3,2] row_mask:0xf bank_mask:0xf
	v_add_f32_dpp v169, v169, v169 quad_perm:[1,0,3,2] row_mask:0xf bank_mask:0xf
	v_add_f32_dpp v170, v170, v170 quad_perm:[1,0,3,2] row_mask:0xf bank_mask:0xf
	v_add_f32_dpp v171, v171, v171 quad_perm:[1,0,3,2] row_mask:0xf bank_mask:0xf
	v_add_f32_dpp v172, v172, v172 quad_perm:[1,0,3,2] row_mask:0xf bank_mask:0xf
	v_add_f32_dpp v173, v173, v173 quad_perm:[1,0,3,2] row_mask:0xf bank_mask:0xf
	v_add_f32_dpp v192, v192, v192 quad_perm:[1,0,3,2] row_mask:0xf bank_mask:0xf
	v_add_f32_dpp v193, v193, v193 quad_perm:[1,0,3,2] row_mask:0xf bank_mask:0xf
	v_add_f32_dpp v168, v168, v168 quad_perm:[2,3,0,1] row_mask:0xf bank_mask:0xf
	v_add_f32_dpp v169, v169, v169 quad_perm:[2,3,0,1] row_mask:0xf bank_mask:0xf
	v_add_f32_dpp v170, v170, v170 quad_perm:[2,3,0,1] row_mask:0xf bank_mask:0xf
	v_add_f32_dpp v171, v171, v171 quad_perm:[2,3,0,1] row_mask:0xf bank_mask:0xf
	v_add_f32_dpp v172, v172, v172 quad_perm:[2,3,0,1] row_mask:0xf bank_mask:0xf
	v_add_f32_dpp v173, v173, v173 quad_perm:[2,3,0,1] row_mask:0xf bank_mask:0xf
	v_add_f32_dpp v192, v192, v192 quad_perm:[2,3,0,1] row_mask:0xf bank_mask:0xf
	v_add_f32_dpp v193, v193, v193 quad_perm:[2,3,0,1] row_mask:0xf bank_mask:0xf
	v_add_f32_dpp v168, v168, v168 row_half_mirror row_mask:0xf bank_mask:0xf
	v_add_f32_dpp v169, v169, v169 row_half_mirror row_mask:0xf bank_mask:0xf
	v_add_f32_dpp v170, v170, v170 row_half_mirror row_mask:0xf bank_mask:0xf
	v_add_f32_dpp v171, v171, v171 row_half_mirror row_mask:0xf bank_mask:0xf
	v_add_f32_dpp v172, v172, v172 row_half_mirror row_mask:0xf bank_mask:0xf
	v_add_f32_dpp v173, v173, v173 row_half_mirror row_mask:0xf bank_mask:0xf
	v_add_f32_dpp v192, v192, v192 row_half_mirror row_mask:0xf bank_mask:0xf
	v_add_f32_dpp v193, v193, v193 row_half_mirror row_mask:0xf bank_mask:0xf
	v_add_f32_dpp v168, v168, v168 row_mirror row_mask:0xf bank_mask:0xf
	v_add_f32_dpp v169, v169, v169 row_mirror row_mask:0xf bank_mask:0xf
	v_add_f32_dpp v170, v170, v170 row_mirror row_mask:0xf bank_mask:0xf
	v_add_f32_dpp v171, v171, v171 row_mirror row_mask:0xf bank_mask:0xf
	v_add_f32_dpp v172, v172, v172 row_mirror row_mask:0xf bank_mask:0xf
	v_add_f32_dpp v173, v173, v173 row_mirror row_mask:0xf bank_mask:0xf
	v_add_f32_dpp v192, v192, v192 row_mirror row_mask:0xf bank_mask:0xf
	v_add_f32_dpp v193, v193, v193 row_mirror row_mask:0xf bank_mask:0xf
	ds_bpermute_b32 v194, v110, v168
	ds_bpermute_b32 v195, v110, v169
	ds_bpermute_b32 v196, v110, v170
	ds_bpermute_b32 v197, v110, v171
	ds_bpermute_b32 v198, v110, v172
	ds_bpermute_b32 v199, v110, v173
	ds_bpermute_b32 v200, v110, v192
	ds_bpermute_b32 v201, v110, v193
	s_waitcnt lgkmcnt(0)
	v_add_f32_e32 v168, v168, v194
	v_add_f32_e32 v169, v169, v195
	v_add_f32_e32 v170, v170, v196
	v_add_f32_e32 v171, v171, v197
	v_add_f32_e32 v172, v172, v198
	v_add_f32_e32 v173, v173, v199
	v_add_f32_e32 v192, v192, v200
	v_add_f32_e32 v193, v193, v201
	ds_bpermute_b32 v194, v111, v168
	ds_bpermute_b32 v195, v111, v169
	ds_bpermute_b32 v196, v111, v170
	ds_bpermute_b32 v197, v111, v171
	ds_bpermute_b32 v198, v111, v172
	ds_bpermute_b32 v199, v111, v173
	ds_bpermute_b32 v200, v111, v192
	ds_bpermute_b32 v201, v111, v193
	s_waitcnt lgkmcnt(0)
; __device__ __forceinline__ void conv_loop(unsigned char* ws_, const float* const* in_, int l_, LAS unsigned char* lds, int tid, int bid, int G) {
;     ...
;                 const float mean = wave_sum((v[0] + v[1]) + (v[2] + v[3])) * (1.0f / 256.0f);
;                 v = v - mean; const float var = wave_sum((v[0] * v[0] + v[1] * v[1]) + (v[2] * v[2] + v[3] * v[3])) * (1.0f / 256.0f);
	v_add_f32_e32 v168, v168, v194
	v_add_f32_e32 v169, v169, v195
	v_add_f32_e32 v170, v170, v196
	v_add_f32_e32 v171, v171, v197
	v_add_f32_e32 v172, v172, v198
	v_add_f32_e32 v173, v173, v199
	v_add_f32_e32 v192, v192, v200
	v_add_f32_e32 v193, v193, v201
	v_fmamk_f32 v124, v168, 0xbb800000, v124
	v_fmamk_f32 v125, v168, 0xbb800000, v125
	v_fmamk_f32 v126, v168, 0xbb800000, v126
	v_fmamk_f32 v127, v168, 0xbb800000, v127
	v_fmamk_f32 v128, v169, 0xbb800000, v128
	v_fmamk_f32 v129, v169, 0xbb800000, v129
	v_fmamk_f32 v130, v169, 0xbb800000, v130
	v_fmamk_f32 v131, v169, 0xbb800000, v131
	v_fmamk_f32 v132, v170, 0xbb800000, v132
	v_fmamk_f32 v133, v170, 0xbb800000, v133
	v_fmamk_f32 v134, v170, 0xbb800000, v134
	v_fmamk_f32 v135, v170, 0xbb800000, v135
	v_fmamk_f32 v148, v171, 0xbb800000, v148
	v_fmamk_f32 v149, v171, 0xbb800000, v149
	v_fmamk_f32 v150, v171, 0xbb800000, v150
	v_fmamk_f32 v151, v171, 0xbb800000, v151
	v_fmamk_f32 v152, v172, 0xbb800000, v152
	v_fmamk_f32 v153, v172, 0xbb800000, v153
	v_fmamk_f32 v154, v172, 0xbb800000, v154
	v_fmamk_f32 v155, v172, 0xbb800000, v155
	v_fmamk_f32 v156, v173, 0xbb800000, v156
	v_fmamk_f32 v157, v173, 0xbb800000, v157
	v_fmamk_f32 v158, v173, 0xbb800000, v158
	v_fmamk_f32 v159, v173, 0xbb800000, v159
	v_fmamk_f32 v160, v192, 0xbb800000, v160
	v_fmamk_f32 v161, v192, 0xbb800000, v161
	v_fmamk_f32 v162, v192, 0xbb800000, v162
	v_fmamk_f32 v163, v192, 0xbb800000, v163
	v_fmamk_f32 v164, v193, 0xbb800000, v164
	v_fmamk_f32 v165, v193, 0xbb800000, v165
	v_fmamk_f32 v166, v193, 0xbb800000, v166
	v_fmamk_f32 v167, v193, 0xbb800000, v167
	v_mul_f32_e32 v168, v125, v125
	v_mul_f32_e32 v194, v124, v124
	v_mul_f32_e32 v169, v129, v129
	v_mul_f32_e32 v195, v128, v128
	v_mul_f32_e32 v170, v133, v133
	v_mul_f32_e32 v196, v132, v132
	v_mul_f32_e32 v171, v149, v149
	v_mul_f32_e32 v197, v148, v148
	v_mul_f32_e32 v172, v153, v153
	v_mul_f32_e32 v198, v152, v152
	v_mul_f32_e32 v173, v157, v157
	v_mul_f32_e32 v199, v156, v156
	v_mul_f32_e32 v192, v161, v161
	v_mul_f32_e32 v200, v160, v160
	v_mul_f32_e32 v193, v165, v165
	v_mul_f32_e32 v201, v164, v164
	v_add_f32_e32 v168, v168, v194
	v_add_f32_e32 v169, v169, v195
	v_add_f32_e32 v170, v170, v196
	v_add_f32_e32 v171, v171, v197
	v_add_f32_e32 v172, v172, v198
	v_add_f32_e32 v173, v173, v199
	v_add_f32_e32 v192, v192, v200
	v_add_f32_e32 v193, v193, v201
	v_mul_f32_e32 v194, v126, v126
	v_mul_f32_e32 v195, v130, v130
	v_mul_f32_e32 v196, v134, v134
	v_mul_f32_e32 v197, v150, v150
	v_mul_f32_e32 v198, v154, v154
	v_mul_f32_e32 v199, v158, v158
	v_mul_f32_e32 v200, v162, v162
	v_mul_f32_e32 v201, v166, v166
	v_mul_f32_e32 v202, v127, v127
	v_mul_f32_e32 v203, v131, v131
	v_mul_f32_e32 v204, v135, v135
	v_mul_f32_e32 v205, v151, v151
	v_add_f32_e32 v194, v194, v202
	v_add_f32_e32 v195, v195, v203
	v_add_f32_e32 v196, v196, v204
	v_add_f32_e32 v197, v197, v205
	v_mul_f32_e32 v202, v155, v155
	v_mul_f32_e32 v203, v159, v159
	v_mul_f32_e32 v204, v163, v163
	v_mul_f32_e32 v205, v167, v167
	v_add_f32_e32 v198, v198, v202
	v_add_f32_e32 v199, v199, v203
	v_add_f32_e32 v200, v200, v204
	v_add_f32_e32 v201, v201, v205
	v_add_f32_e32 v168, v168, v194
	v_add_f32_e32 v169, v169, v195
	v_add_f32_e32 v170, v170, v196
	v_add_f32_e32 v171, v171, v197
	v_add_f32_e32 v172, v172, v198
	v_add_f32_e32 v173, v173, v199
	v_add_f32_e32 v192, v192, v200
	v_add_f32_e32 v193, v193, v201
	v_add_f32_dpp v168, v168, v168 quad_perm:[1,0,3,2] row_mask:0xf bank_mask:0xf
	v_add_f32_dpp v169, v169, v169 quad_perm:[1,0,3,2] row_mask:0xf bank_mask:0xf
	v_add_f32_dpp v170, v170, v170 quad_perm:[1,0,3,2] row_mask:0xf bank_mask:0xf
	v_add_f32_dpp v171, v171, v171 quad_perm:[1,0,3,2] row_mask:0xf bank_mask:0xf
	v_add_f32_dpp v172, v172, v172 quad_perm:[1,0,3,2] row_mask:0xf bank_mask:0xf
	v_add_f32_dpp v173, v173, v173 quad_perm:[1,0,3,2] row_mask:0xf bank_mask:0xf
	v_add_f32_dpp v192, v192, v192 quad_perm:[1,0,3,2] row_mask:0xf bank_mask:0xf
	v_add_f32_dpp v193, v193, v193 quad_perm:[1,0,3,2] row_mask:0xf bank_mask:0xf
	v_add_f32_dpp v168, v168, v168 quad_perm:[2,3,0,1] row_mask:0xf bank_mask:0xf
	v_add_f32_dpp v169, v169, v169 quad_perm:[2,3,0,1] row_mask:0xf bank_mask:0xf
	v_add_f32_dpp v170, v170, v170 quad_perm:[2,3,0,1] row_mask:0xf bank_mask:0xf
	v_add_f32_dpp v171, v171, v171 quad_perm:[2,3,0,1] row_mask:0xf bank_mask:0xf
	v_add_f32_dpp v172, v172, v172 quad_perm:[2,3,0,1] row_mask:0xf bank_mask:0xf
	v_add_f32_dpp v173, v173, v173 quad_perm:[2,3,0,1] row_mask:0xf bank_mask:0xf
	v_add_f32_dpp v192, v192, v192 quad_perm:[2,3,0,1] row_mask:0xf bank_mask:0xf
	v_add_f32_dpp v193, v193, v193 quad_perm:[2,3,0,1] row_mask:0xf bank_mask:0xf
	v_add_f32_dpp v168, v168, v168 row_half_mirror row_mask:0xf bank_mask:0xf
	v_add_f32_dpp v169, v169, v169 row_half_mirror row_mask:0xf bank_mask:0xf
	v_add_f32_dpp v170, v170, v170 row_half_mirror row_mask:0xf bank_mask:0xf
	v_add_f32_dpp v171, v171, v171 row_half_mirror row_mask:0xf bank_mask:0xf
	v_add_f32_dpp v172, v172, v172 row_half_mirror row_mask:0xf bank_mask:0xf
	v_add_f32_dpp v173, v173, v173 row_half_mirror row_mask:0xf bank_mask:0xf
	v_add_f32_dpp v192, v192, v192 row_half_mirror row_mask:0xf bank_mask:0xf
	v_add_f32_dpp v193, v193, v193 row_half_mirror row_mask:0xf bank_mask:0xf
	v_add_f32_dpp v168, v168, v168 row_mirror row_mask:0xf bank_mask:0xf
	v_add_f32_dpp v169, v169, v169 row_mirror row_mask:0xf bank_mask:0xf
	v_add_f32_dpp v170, v170, v170 row_mirror row_mask:0xf bank_mask:0xf
	v_add_f32_dpp v171, v171, v171 row_mirror row_mask:0xf bank_mask:0xf
	v_add_f32_dpp v172, v172, v172 row_mirror row_mask:0xf bank_mask:0xf
	v_add_f32_dpp v173, v173, v173 row_mirror row_mask:0xf bank_mask:0xf
	v_add_f32_dpp v192, v192, v192 row_mirror row_mask:0xf bank_mask:0xf
	v_add_f32_dpp v193, v193, v193 row_mirror row_mask:0xf bank_mask:0xf
	ds_bpermute_b32 v194, v110, v168
	ds_bpermute_b32 v195, v110, v169
	ds_bpermute_b32 v196, v110, v170
	ds_bpermute_b32 v197, v110, v171
	ds_bpermute_b32 v198, v110, v172
	ds_bpermute_b32 v199, v110, v173
	ds_bpermute_b32 v200, v110, v192
	ds_bpermute_b32 v201, v110, v193
	s_waitcnt lgkmcnt(0)
; __device__ __forceinline__ float sigmoidf_(float x) { return __builtin_amdgcn_rcpf(1.f + __expf(-x)); }
; __device__ __forceinline__ void conv_loop(unsigned char* ws_, const float* const* in_, int l_, LAS unsigned char* lds, int tid, int bid, int G) {
;     ...
;                 const float mean = wave_sum((v[0] + v[1]) + (v[2] + v[3])) * (1.0f / 256.0f);
;                 v = v - mean; const float var = wave_sum((v[0] * v[0] + v[1] * v[1]) + (v[2] * v[2] + v[3] * v[3])) * (1.0f / 256.0f);
;                 const float rstd = rsqrtf(var + LN_EPS); f32x4 y = v * rstd * gg + bb;
; #pragma unroll
;                 for (int e = 0; e < 4; ++e) y[e] = y[e] * sigmoidf_(y[e]);
	v_add_f32_e32 v168, v168, v194
	v_add_f32_e32 v169, v169, v195
	v_add_f32_e32 v170, v170, v196
	v_add_f32_e32 v171, v171, v197
	v_add_f32_e32 v172, v172, v198
	v_add_f32_e32 v173, v173, v199
	v_add_f32_e32 v192, v192, v200
	v_add_f32_e32 v193, v193, v201
	ds_bpermute_b32 v194, v111, v168
	ds_bpermute_b32 v195, v111, v169
	ds_bpermute_b32 v196, v111, v170
	ds_bpermute_b32 v197, v111, v171
	ds_bpermute_b32 v198, v111, v172
	ds_bpermute_b32 v199, v111, v173
	ds_bpermute_b32 v200, v111, v192
	ds_bpermute_b32 v201, v111, v193
	s_waitcnt lgkmcnt(0)
	v_add_f32_e32 v168, v168, v194
	v_add_f32_e32 v169, v169, v195
	v_add_f32_e32 v170, v170, v196
	v_add_f32_e32 v171, v171, v197
	v_add_f32_e32 v172, v172, v198
	v_add_f32_e32 v173, v173, v199
	v_add_f32_e32 v192, v192, v200
	v_add_f32_e32 v193, v193, v201
	v_fmamk_f32 v168, v168, 0x3b800000, v176
	v_fmamk_f32 v169, v169, 0x3b800000, v176
	v_fmamk_f32 v170, v170, 0x3b800000, v176
	v_fmamk_f32 v171, v171, 0x3b800000, v176
	v_fmamk_f32 v172, v172, 0x3b800000, v176
	v_fmamk_f32 v173, v173, 0x3b800000, v176
	v_fmamk_f32 v192, v192, 0x3b800000, v176
	v_fmamk_f32 v193, v193, 0x3b800000, v176
	v_rsq_f32_e32 v168, v168
	v_rsq_f32_e32 v169, v169
	v_rsq_f32_e32 v170, v170
	v_rsq_f32_e32 v171, v171
	v_rsq_f32_e32 v172, v172
	v_rsq_f32_e32 v173, v173
	v_rsq_f32_e32 v192, v192
	v_rsq_f32_e32 v193, v193
	v_mul_f32_e32 v124, v124, v168
	v_mul_f32_e32 v125, v125, v168
	v_mul_f32_e32 v126, v126, v168
	v_mul_f32_e32 v127, v127, v168
	v_mul_f32_e32 v128, v128, v169
	v_mul_f32_e32 v129, v129, v169
	v_mul_f32_e32 v130, v130, v169
	v_mul_f32_e32 v131, v131, v169
	v_mul_f32_e32 v132, v132, v170
	v_mul_f32_e32 v133, v133, v170
	v_mul_f32_e32 v134, v134, v170
	v_mul_f32_e32 v135, v135, v170
	v_mul_f32_e32 v148, v148, v171
	v_mul_f32_e32 v149, v149, v171
	v_mul_f32_e32 v150, v150, v171
	v_mul_f32_e32 v151, v151, v171
	v_mul_f32_e32 v152, v152, v172
	v_mul_f32_e32 v153, v153, v172
	v_mul_f32_e32 v154, v154, v172
	v_mul_f32_e32 v155, v155, v172
	v_mul_f32_e32 v156, v156, v173
	v_mul_f32_e32 v157, v157, v173
	v_mul_f32_e32 v158, v158, v173
	v_mul_f32_e32 v159, v159, v173
	v_mul_f32_e32 v160, v160, v192
	v_mul_f32_e32 v161, v161, v192
	v_mul_f32_e32 v162, v162, v192
	v_mul_f32_e32 v163, v163, v192
	v_mul_f32_e32 v164, v164, v193
	v_mul_f32_e32 v165, v165, v193
	v_mul_f32_e32 v166, v166, v193
	v_mul_f32_e32 v167, v167, v193
	v_pk_fma_f32 v[124:125], v[2:3], v[124:125], v[6:7]
	v_pk_fma_f32 v[126:127], v[4:5], v[126:127], v[8:9]
	v_pk_fma_f32 v[128:129], v[2:3], v[128:129], v[6:7]
	v_pk_fma_f32 v[130:131], v[4:5], v[130:131], v[8:9]
	v_pk_fma_f32 v[132:133], v[2:3], v[132:133], v[6:7]
	v_pk_fma_f32 v[134:135], v[4:5], v[134:135], v[8:9]
	v_pk_fma_f32 v[148:149], v[2:3], v[148:149], v[6:7]
	v_pk_fma_f32 v[150:151], v[4:5], v[150:151], v[8:9]
	v_pk_fma_f32 v[152:153], v[2:3], v[152:153], v[6:7]
	v_pk_fma_f32 v[154:155], v[4:5], v[154:155], v[8:9]
	v_pk_fma_f32 v[156:157], v[2:3], v[156:157], v[6:7]
	v_pk_fma_f32 v[158:159], v[4:5], v[158:159], v[8:9]
	v_pk_fma_f32 v[160:161], v[2:3], v[160:161], v[6:7]
	v_pk_fma_f32 v[162:163], v[4:5], v[162:163], v[8:9]
	v_pk_fma_f32 v[164:165], v[2:3], v[164:165], v[6:7]
	v_pk_fma_f32 v[166:167], v[4:5], v[166:167], v[8:9]
	v_pk_mul_f32 v[168:169], v[124:125], s[78:79] op_sel_hi:[1,0]
	v_pk_mul_f32 v[170:171], v[126:127], s[78:79] op_sel_hi:[1,0]
	v_pk_mul_f32 v[172:173], v[128:129], s[78:79] op_sel_hi:[1,0]
	v_pk_mul_f32 v[192:193], v[130:131], s[78:79] op_sel_hi:[1,0]
	v_pk_mul_f32 v[194:195], v[132:133], s[78:79] op_sel_hi:[1,0]
	v_pk_mul_f32 v[196:197], v[134:135], s[78:79] op_sel_hi:[1,0]
	v_pk_mul_f32 v[198:199], v[148:149], s[78:79] op_sel_hi:[1,0]
	v_pk_mul_f32 v[200:201], v[150:151], s[78:79] op_sel_hi:[1,0]
	v_exp_f32_e32 v168, v168
	v_exp_f32_e32 v169, v169
	v_exp_f32_e32 v170, v170
	v_exp_f32_e32 v171, v171
	v_exp_f32_e32 v172, v172
	v_exp_f32_e32 v173, v173
	v_exp_f32_e32 v192, v192
	v_exp_f32_e32 v193, v193
	v_exp_f32_e32 v194, v194
	v_exp_f32_e32 v195, v195
	v_exp_f32_e32 v196, v196
	v_exp_f32_e32 v197, v197
	v_exp_f32_e32 v198, v198
	v_exp_f32_e32 v199, v199
	v_exp_f32_e32 v200, v200
	v_exp_f32_e32 v201, v201
	v_pk_add_f32 v[168:169], v[168:169], s[80:81] op_sel_hi:[1,0]
	v_pk_add_f32 v[170:171], v[170:171], s[80:81] op_sel_hi:[1,0]
	v_pk_add_f32 v[172:173], v[172:173], s[80:81] op_sel_hi:[1,0]
	v_pk_add_f32 v[192:193], v[192:193], s[80:81] op_sel_hi:[1,0]
	v_pk_add_f32 v[194:195], v[194:195], s[80:81] op_sel_hi:[1,0]
	v_pk_add_f32 v[196:197], v[196:197], s[80:81] op_sel_hi:[1,0]
	v_pk_add_f32 v[198:199], v[198:199], s[80:81] op_sel_hi:[1,0]
	v_pk_add_f32 v[200:201], v[200:201], s[80:81] op_sel_hi:[1,0]
	v_rcp_f32_e32 v168, v168
; __device__ __forceinline__ unsigned cvt_pk_bf16(float lo, float hi) { unsigned r; asm volatile("v_cvt_pk_bf16_f32 %0, %1, %2" : "=v"(r) : "v"(lo), "v"(hi)); return r; }
; __device__ __forceinline__ float sigmoidf_(float x) { return __builtin_amdgcn_rcpf(1.f + __expf(-x)); }
; __device__ __forceinline__ void conv_loop(unsigned char* ws_, const float* const* in_, int l_, LAS unsigned char* lds, int tid, int bid, int G) {
;     ...
;             for (int o = 0; o < 32; ++o) U[ring94(ring94(rb + o)) * 256 + cch] = acc[o];
;     ...
;                 const float rstd = rsqrtf(var + LN_EPS); f32x4 y = v * rstd * gg + bb;
; #pragma unroll
;                 for (int e = 0; e < 4; ++e) y[e] = y[e] * sigmoidf_(y[e]);
;                 u32x2 wv2; wv2.x = cvt_pk_bf16(y[0], y[1]); wv2.y = cvt_pk_bf16(y[2], y[3]);
;                 *(u32x2*)(X.MIX + ((size_t)b * SEQ + t0 + tok) * DM + AW + 4 * lane) = wv2; }
	v_rcp_f32_e32 v169, v169
	v_rcp_f32_e32 v170, v170
	v_rcp_f32_e32 v171, v171
	v_rcp_f32_e32 v172, v172
	v_rcp_f32_e32 v173, v173
	v_rcp_f32_e32 v192, v192
	v_rcp_f32_e32 v193, v193
	v_rcp_f32_e32 v194, v194
	v_rcp_f32_e32 v195, v195
	v_rcp_f32_e32 v196, v196
	v_rcp_f32_e32 v197, v197
	v_rcp_f32_e32 v198, v198
	v_rcp_f32_e32 v199, v199
	v_rcp_f32_e32 v200, v200
	v_rcp_f32_e32 v201, v201
	v_pk_mul_f32 v[124:125], v[124:125], v[168:169]
	v_pk_mul_f32 v[126:127], v[126:127], v[170:171]
	v_pk_mul_f32 v[128:129], v[128:129], v[172:173]
	v_pk_mul_f32 v[130:131], v[130:131], v[192:193]
	v_pk_mul_f32 v[132:133], v[132:133], v[194:195]
	v_pk_mul_f32 v[134:135], v[134:135], v[196:197]
	v_pk_mul_f32 v[148:149], v[148:149], v[198:199]
	v_pk_mul_f32 v[150:151], v[150:151], v[200:201]
	v_cvt_pk_bf16_f32 v124, v124, v125
	v_cvt_pk_bf16_f32 v125, v126, v127
	v_cvt_pk_bf16_f32 v128, v128, v129
	v_cvt_pk_bf16_f32 v129, v130, v131
	v_cvt_pk_bf16_f32 v132, v132, v133
	v_cvt_pk_bf16_f32 v133, v134, v135
	v_cvt_pk_bf16_f32 v148, v148, v149
	v_cvt_pk_bf16_f32 v149, v150, v151
	global_store_dwordx2 v[206:207], v[124:125], off
	global_store_dwordx2 v[206:207], v[128:129], off offset:2048
	global_store_dwordx2 v[208:209], v[132:133], off
	global_store_dwordx2 v[208:209], v[148:149], off offset:2048
	v_pk_mul_f32 v[168:169], v[152:153], s[78:79] op_sel_hi:[1,0]
	v_pk_mul_f32 v[170:171], v[154:155], s[78:79] op_sel_hi:[1,0]
	v_pk_mul_f32 v[172:173], v[156:157], s[78:79] op_sel_hi:[1,0]
	v_pk_mul_f32 v[192:193], v[158:159], s[78:79] op_sel_hi:[1,0]
	v_pk_mul_f32 v[194:195], v[160:161], s[78:79] op_sel_hi:[1,0]
	v_pk_mul_f32 v[196:197], v[162:163], s[78:79] op_sel_hi:[1,0]
	v_pk_mul_f32 v[198:199], v[164:165], s[78:79] op_sel_hi:[1,0]
	v_pk_mul_f32 v[200:201], v[166:167], s[78:79] op_sel_hi:[1,0]
	v_exp_f32_e32 v168, v168
	v_exp_f32_e32 v169, v169
	v_exp_f32_e32 v170, v170
	v_exp_f32_e32 v171, v171
	v_exp_f32_e32 v172, v172
	v_exp_f32_e32 v173, v173
	v_exp_f32_e32 v192, v192
	v_exp_f32_e32 v193, v193
	v_exp_f32_e32 v194, v194
	v_exp_f32_e32 v195, v195
	v_exp_f32_e32 v196, v196
	v_exp_f32_e32 v197, v197
	v_exp_f32_e32 v198, v198
	v_exp_f32_e32 v199, v199
	v_exp_f32_e32 v200, v200
	v_exp_f32_e32 v201, v201
	v_pk_add_f32 v[168:169], v[168:169], s[80:81] op_sel_hi:[1,0]
	v_pk_add_f32 v[170:171], v[170:171], s[80:81] op_sel_hi:[1,0]
	v_pk_add_f32 v[172:173], v[172:173], s[80:81] op_sel_hi:[1,0]
	v_pk_add_f32 v[192:193], v[192:193], s[80:81] op_sel_hi:[1,0]
	v_pk_add_f32 v[194:195], v[194:195], s[80:81] op_sel_hi:[1,0]
	v_pk_add_f32 v[196:197], v[196:197], s[80:81] op_sel_hi:[1,0]
	v_pk_add_f32 v[198:199], v[198:199], s[80:81] op_sel_hi:[1,0]
	v_pk_add_f32 v[200:201], v[200:201], s[80:81] op_sel_hi:[1,0]
	v_rcp_f32_e32 v168, v168
	v_rcp_f32_e32 v169, v169
	v_rcp_f32_e32 v170, v170
	v_rcp_f32_e32 v171, v171
	v_rcp_f32_e32 v172, v172
	v_rcp_f32_e32 v173, v173
	v_rcp_f32_e32 v192, v192
	v_rcp_f32_e32 v193, v193
	v_rcp_f32_e32 v194, v194
	v_rcp_f32_e32 v195, v195
	v_rcp_f32_e32 v196, v196
	v_rcp_f32_e32 v197, v197
	v_rcp_f32_e32 v198, v198
	v_rcp_f32_e32 v199, v199
	v_rcp_f32_e32 v200, v200
	v_rcp_f32_e32 v201, v201
	v_pk_mul_f32 v[152:153], v[152:153], v[168:169]
	v_pk_mul_f32 v[154:155], v[154:155], v[170:171]
	v_pk_mul_f32 v[156:157], v[156:157], v[172:173]
	v_pk_mul_f32 v[158:159], v[158:159], v[192:193]
	v_pk_mul_f32 v[160:161], v[160:161], v[194:195]
	v_pk_mul_f32 v[162:163], v[162:163], v[196:197]
	v_pk_mul_f32 v[164:165], v[164:165], v[198:199]
	v_pk_mul_f32 v[166:167], v[166:167], v[200:201]
	v_cvt_pk_bf16_f32 v152, v152, v153
	v_cvt_pk_bf16_f32 v153, v154, v155
	v_cvt_pk_bf16_f32 v156, v156, v157
	v_cvt_pk_bf16_f32 v157, v158, v159
	v_cvt_pk_bf16_f32 v160, v160, v161
	v_cvt_pk_bf16_f32 v161, v162, v163
	v_cvt_pk_bf16_f32 v164, v164, v165
	v_cvt_pk_bf16_f32 v165, v166, v167
	global_store_dwordx2 v[210:211], v[152:153], off
	global_store_dwordx2 v[210:211], v[156:157], off offset:2048
	global_store_dwordx2 v[212:213], v[160:161], off
	global_store_dwordx2 v[212:213], v[164:165], off offset:2048
	s_cmp_eq_u32 s27, 0
	s_barrier
	s_cbranch_scc1 .LBB0_292
	ds_write_b32 v229, v214 offset:0
	ds_write_b32 v229, v215 offset:1024
	ds_write_b32 v229, v216 offset:2048
	ds_write_b32 v229, v217 offset:3072
	ds_write_b32 v229, v218 offset:4096
	ds_write_b32 v229, v219 offset:5120
	ds_write_b32 v229, v220 offset:6144
	ds_write_b32 v229, v221 offset:7168
	ds_write_b32 v229, v222 offset:8192
	ds_write_b32 v229, v223 offset:9216
	ds_write_b32 v229, v224 offset:10240
	ds_write_b32 v229, v225 offset:11264
	ds_write_b32 v229, v226 offset:12288
	ds_write_b32 v229, v227 offset:13312
	ds_write_b32 v229, v228 offset:14336
